# GEMM P1/P4/P11: row-scale loads before the K-loop, no vmcnt wait in the epilogue, and the first two K-loop waits of units after the first relaxed to allow the epilogue's stores/loads outstanding (in-o
# speedup vs baseline: 1.0117x; 1.0023x over previous
; #define PG8_STAGE(bufoff, gbase, voff) do { _Pragma("unroll") for (int _i = 0; _i < 2; ++_i) \
;         __builtin_amdgcn_global_load_lds((const unsigned*)((const char*)(gbase) + (voff)[_i]), (PG8_LAS unsigned*)(lds + (bufoff) + ldsw + _i * 8192), 16, 0, 0); } while (0)
; #define PG8_LDA(dst, b, h) do { _Pragma("unroll") for (int m = 0; m < 4; ++m) _Pragma("unroll") for (int k = 0; k < 2; ++k) dst[m][k] = *(const PG8_LAS bf16x8*)(lds + PG8_SA(b, h) + aoff + m * 2048 + k * 1024); } while (0)
; #define PG8_LDB(dst, b, h) do { _Pragma("unroll") for (int n = 0; n < 2; ++n) _Pragma("unroll") for (int k = 0; k < 2; ++k) dst[n][k] = *(const PG8_LAS bf16x8*)(lds + PG8_SB(b, h) + boff + n * 2048 + k * 1024); } while (0)
; #define PG8_SCHED __builtin_amdgcn_sched_barrier(0)
; template <class Epi, class Sched, bool ALIGN_EPI = false, bool SP2 = false>
; __device__ __forceinline__ void gemm_phase(PG8_LAS unsigned char* lds, const Gemm g, const Sched& S, const Epi& E) {
;     ...
;         const bool has_next = S.next(ui + 1, nxt);
;         const char* nA = has_next ? (const char*)g.A + (size_t)nxt.pm * tstep : cA; const char* nB = has_next ? (const char*)g.Bt + (size_t)nxt.pn * tstep : cB;
;         for (int t = 0; t < nt; t += 2) {
;             const bool last = (t == nt - 2);
;             const char* a1 = cA + (size_t)(t + 1) * kstep;
;             const char* a2 = last ? nA : cA + (size_t)(t + 2) * kstep; const char* b2 = last ? nB : cB + (size_t)(t + 2) * kstep;
;             const char* a3 = a2 + kstep; const char* b3 = b2 + kstep;
;             if (last && has_next) S.a_ready(nxt);
;             if constexpr (SP2) {
;             PG8_LDB(B0, 0, 0); PG8_LDB(B1, 0, 1); PG8_SCHED; PG8_LDA(At, 0, 0); PG8_STAGE(PG8_SA(1, 1), a1 + hstep, voffA);
;     ...
; #pragma unroll
;         for (int a = 0; a < 2; ++a)
; #pragma unroll
;             for (int b = 0; b < 2; ++b)
; #pragma unroll
;                 for (int m = 0; m < 4; ++m)
; #pragma unroll
;                     for (int n = 0; n < 2; ++n) acc[a][b][m][n] = (f32x4){0.f, 0.f, 0.f, 0.f};
;         cur = nxt; cA = nA; cB = nB; ++ui;
.LBB0_292:
	s_ashr_i32 s17, s16, 31
	s_lshl_b64 s[18:19], s[16:17], 19
	v_readlane_b32 s20, v253, 45
	v_readlane_b32 s21, v253, 46
	s_add_u32 s18, s20, s18
	s_addc_u32 s19, s21, s19
	s_and_b64 s[20:21], s[0:1], exec
	s_cselect_b32 s17, s19, s25
	s_cselect_b32 s46, s18, s24
	s_ashr_i32 s15, s14, 31
	s_lshl_b64 s[20:21], s[14:15], 19
	s_add_u32 s20, s64, s20
	s_addc_u32 s21, s65, s21
	s_and_b64 s[28:29], s[0:1], exec
	s_cselect_b32 s15, s21, s27
	s_cselect_b32 s47, s20, s26
	s_add_u32 s24, s24, 0x40080
	s_addc_u32 s25, s25, 0
	s_add_u32 s48, s26, 0x100
	v_mov_b32_e32 v0, 0
	s_addc_u32 s49, s27, 0
	s_mov_b32 s50, -2
	v_mov_b32_e32 v1, v0
	v_mov_b32_e32 v2, v0
	v_mov_b32_e32 v3, v0
	v_mov_b32_e32 v4, v0
	v_mov_b32_e32 v5, v0
	v_mov_b32_e32 v6, v0
	v_mov_b32_e32 v7, v0
	v_mov_b32_e32 v16, v0
	v_mov_b32_e32 v17, v0
	v_mov_b32_e32 v18, v0
	v_mov_b32_e32 v19, v0
	v_mov_b32_e32 v20, v0
	v_mov_b32_e32 v21, v0
	v_mov_b32_e32 v22, v0
	v_mov_b32_e32 v23, v0
	v_mov_b32_e32 v32, v0
	v_mov_b32_e32 v33, v0
	v_mov_b32_e32 v34, v0
	v_mov_b32_e32 v35, v0
	v_mov_b32_e32 v36, v0
	v_mov_b32_e32 v37, v0
	v_mov_b32_e32 v38, v0
	v_mov_b32_e32 v39, v0
	v_mov_b32_e32 v48, v0
	v_mov_b32_e32 v49, v0
	v_mov_b32_e32 v50, v0
	v_mov_b32_e32 v51, v0
	v_mov_b32_e32 v52, v0
	v_mov_b32_e32 v53, v0
	v_mov_b32_e32 v54, v0
	v_mov_b32_e32 v55, v0
	v_mov_b32_e32 v8, v0
	v_mov_b32_e32 v9, v0
	v_mov_b32_e32 v10, v0
	v_mov_b32_e32 v11, v0
	v_mov_b32_e32 v12, v0
	v_mov_b32_e32 v13, v0
	v_mov_b32_e32 v14, v0
	v_mov_b32_e32 v15, v0
	v_mov_b32_e32 v24, v0
	v_mov_b32_e32 v25, v0
	v_mov_b32_e32 v26, v0
	v_mov_b32_e32 v27, v0
	v_mov_b32_e32 v28, v0
	v_mov_b32_e32 v29, v0
	v_mov_b32_e32 v30, v0
	v_mov_b32_e32 v31, v0
	v_mov_b32_e32 v40, v0
	v_mov_b32_e32 v41, v0
	v_mov_b32_e32 v42, v0
	v_mov_b32_e32 v43, v0
	v_mov_b32_e32 v44, v0
	v_mov_b32_e32 v45, v0
	v_mov_b32_e32 v46, v0
	v_mov_b32_e32 v47, v0
	v_mov_b32_e32 v56, v0
	v_mov_b32_e32 v57, v0
	v_mov_b32_e32 v58, v0
	v_mov_b32_e32 v59, v0
	v_mov_b32_e32 v60, v0
	v_mov_b32_e32 v61, v0
	v_mov_b32_e32 v62, v0
	v_mov_b32_e32 v63, v0
	v_mov_b32_e32 v64, v0
	v_mov_b32_e32 v65, v0
	v_mov_b32_e32 v66, v0
	v_mov_b32_e32 v67, v0
	v_mov_b32_e32 v68, v0
	v_mov_b32_e32 v69, v0
	v_mov_b32_e32 v70, v0
	v_mov_b32_e32 v71, v0
	v_mov_b32_e32 v80, v0
	v_mov_b32_e32 v81, v0
	v_mov_b32_e32 v82, v0
	v_mov_b32_e32 v83, v0
	v_mov_b32_e32 v84, v0
	v_mov_b32_e32 v85, v0
	v_mov_b32_e32 v86, v0
	v_mov_b32_e32 v87, v0
	v_mov_b32_e32 v96, v0
	v_mov_b32_e32 v97, v0
	v_mov_b32_e32 v98, v0
	v_mov_b32_e32 v99, v0
	v_mov_b32_e32 v100, v0
	v_mov_b32_e32 v101, v0
	v_mov_b32_e32 v102, v0
	v_mov_b32_e32 v103, v0
	v_mov_b32_e32 v112, v0
	v_mov_b32_e32 v113, v0
	v_mov_b32_e32 v114, v0
	v_mov_b32_e32 v115, v0
	v_mov_b32_e32 v116, v0
	v_mov_b32_e32 v117, v0
	v_mov_b32_e32 v118, v0
	v_mov_b32_e32 v119, v0
	v_mov_b32_e32 v72, v0
	v_mov_b32_e32 v73, v0
	v_mov_b32_e32 v74, v0
	v_mov_b32_e32 v75, v0
	v_mov_b32_e32 v76, v0
	v_mov_b32_e32 v77, v0
	v_mov_b32_e32 v78, v0
	v_mov_b32_e32 v79, v0
	v_mov_b32_e32 v88, v0
	v_mov_b32_e32 v89, v0
	v_mov_b32_e32 v90, v0
	v_mov_b32_e32 v91, v0
	v_mov_b32_e32 v92, v0
	v_mov_b32_e32 v93, v0
	v_mov_b32_e32 v94, v0
	v_mov_b32_e32 v95, v0
	v_mov_b32_e32 v104, v0
	v_mov_b32_e32 v105, v0
	v_mov_b32_e32 v106, v0
	v_mov_b32_e32 v107, v0
	v_mov_b32_e32 v108, v0
	v_mov_b32_e32 v109, v0
	v_mov_b32_e32 v110, v0
	v_mov_b32_e32 v111, v0
	v_mov_b32_e32 v120, v0
	v_mov_b32_e32 v121, v0
	v_mov_b32_e32 v122, v0
	v_mov_b32_e32 v123, v0
	v_mov_b32_e32 v124, v0
	v_mov_b32_e32 v125, v0
	v_mov_b32_e32 v126, v0
	v_mov_b32_e32 v127, v0
	s_cmp_eq_u32 s37, 1
	s_cselect_b32 s101, 0x7fffffff, -2
.LBB0_293:
	ds_read_b128 v[144:147], v151
	ds_read_b128 v[154:157], v151 offset:1024
	ds_read_b128 v[158:161], v151 offset:2048
	ds_read_b128 v[162:165], v151 offset:3072
	ds_read_b128 v[166:169], v152
	ds_read_b128 v[170:173], v152 offset:1024
	ds_read_b128 v[174:177], v152 offset:2048
	ds_read_b128 v[178:181], v152 offset:3072
	s_add_u32 s26, s24, 0xfffc0080
	s_addc_u32 s27, s25, -1
	s_cmp_eq_u32 s50, 12
	s_cselect_b32 s29, s17, s27
	s_cselect_b32 s28, s46, s26
	s_cselect_b32 s27, s15, s49
	s_cselect_b32 s26, s47, s48
	v_lshl_add_u64 v[194:195], s[24:25], 0, v[136:137]
	s_add_i32 m0, s23, 0xc000
	ds_read_b128 v[182:185], v153
	ds_read_b128 v[186:189], v153 offset:1024
	ds_read_b128 v[190:193], v153 offset:2048
	ds_read_b128 v[198:201], v153 offset:3072
	ds_read_b128 v[202:205], v153 offset:4096
	ds_read_b128 v[206:209], v153 offset:5120
	ds_read_b128 v[210:213], v153 offset:6144
	ds_read_b128 v[214:217], v153 offset:7168
	global_load_lds_dwordx4 v[194:195], off
	v_lshl_add_u64 v[194:195], s[24:25], 0, v[138:139]
	s_add_i32 m0, s23, 0xe000
	s_nop 0
	global_load_lds_dwordx4 v[194:195], off
	s_cmp_eq_u32 s50, s101
	s_cbranch_scc1 .Lrw0_r0
	s_waitcnt vmcnt(8)
; #define PG8_STAGE(bufoff, gbase, voff) do { _Pragma("unroll") for (int _i = 0; _i < 2; ++_i) \
;         __builtin_amdgcn_global_load_lds((const unsigned*)((const char*)(gbase) + (voff)[_i]), (PG8_LAS unsigned*)(lds + (bufoff) + ldsw + _i * 8192), 16, 0, 0); } while (0)
; #define PG8_LDA(dst, b, h) do { _Pragma("unroll") for (int m = 0; m < 4; ++m) _Pragma("unroll") for (int k = 0; k < 2; ++k) dst[m][k] = *(const PG8_LAS bf16x8*)(lds + PG8_SA(b, h) + aoff + m * 2048 + k * 1024); } while (0)
; #define PG8_LDB(dst, b, h) do { _Pragma("unroll") for (int n = 0; n < 2; ++n) _Pragma("unroll") for (int k = 0; k < 2; ++k) dst[n][k] = *(const PG8_LAS bf16x8*)(lds + PG8_SB(b, h) + boff + n * 2048 + k * 1024); } while (0)
; #define PG8_MMA(ai, bj, At, Bt) do { __builtin_amdgcn_s_setprio(1); _Pragma("unroll") for (int m = 0; m < 4; ++m) _Pragma("unroll") for (int n = 0; n < 2; ++n) _Pragma("unroll") for (int k = 0; k < 2; ++k) \
;         acc[ai][bj][m][n] = __builtin_amdgcn_mfma_f32_16x16x32_bf16(Bt[n][k], At[m][k], acc[ai][bj][m][n], 0, 0, 0); __builtin_amdgcn_s_setprio(0); } while (0)
; #define PG8_WAIT_V(n) asm volatile("s_waitcnt vmcnt(" #n ")" ::: "memory")
; #define PG8_WAIT_L(n) asm volatile("s_waitcnt lgkmcnt(" #n ")" ::: "memory")
; #define PG8_BAR __builtin_amdgcn_s_barrier()
; #define PG8_SCHED __builtin_amdgcn_sched_barrier(0)
; template <class Epi, class Sched, bool ALIGN_EPI = false, bool SP2 = false>
; __device__ __forceinline__ void gemm_phase(PG8_LAS unsigned char* lds, const Gemm g, const Sched& S, const Epi& E) {
;     ...
;             PG8_LDB(B0, 0, 0); PG8_LDB(B1, 0, 1); PG8_SCHED; PG8_LDA(At, 0, 0); PG8_STAGE(PG8_SA(1, 1), a1 + hstep, voffA);
;             PG8_WAIT_V(8); PG8_WAIT_L(0); PG8_BAR; PG8_MMA(0, 0, At, B0); PG8_MMA(0, 1, At, B1); PG8_BAR; PG8_SCHED;
;             PG8_LDA(At, 0, 1); PG8_STAGE(PG8_SB(0, 0), b2, voffB); PG8_STAGE(PG8_SB(0, 1), b2 + hstep, voffB); PG8_STAGE(PG8_SA(0, 0), a2, voffA);
;             PG8_WAIT_V(8); PG8_WAIT_L(0); PG8_BAR; PG8_MMA(1, 0, At, B0); PG8_MMA(1, 1, At, B1); PG8_BAR; PG8_SCHED;
.Lrw0_b0:
	s_waitcnt lgkmcnt(0)
	s_barrier
	s_setprio 1
	s_waitcnt lgkmcnt(0)
	v_mfma_f32_16x16x32_bf16 v[124:127], v[144:147], v[182:185], v[124:127]
	v_mfma_f32_16x16x32_bf16 v[120:123], v[158:161], v[182:185], v[120:123]
	v_mfma_f32_16x16x32_bf16 v[108:111], v[144:147], v[190:193], v[108:111]
	v_mfma_f32_16x16x32_bf16 v[104:107], v[158:161], v[190:193], v[104:107]
	v_mfma_f32_16x16x32_bf16 v[92:95], v[144:147], v[202:205], v[92:95]
	v_mfma_f32_16x16x32_bf16 v[88:91], v[158:161], v[202:205], v[88:91]
	v_mfma_f32_16x16x32_bf16 v[76:79], v[144:147], v[210:213], v[76:79]
	v_mfma_f32_16x16x32_bf16 v[72:75], v[158:161], v[210:213], v[72:75]
	v_mfma_f32_16x16x32_bf16 v[124:127], v[154:157], v[186:189], v[124:127]
	v_mfma_f32_16x16x32_bf16 v[120:123], v[162:165], v[186:189], v[120:123]
	v_mfma_f32_16x16x32_bf16 v[108:111], v[154:157], v[198:201], v[108:111]
	v_mfma_f32_16x16x32_bf16 v[104:107], v[162:165], v[198:201], v[104:107]
	v_mfma_f32_16x16x32_bf16 v[92:95], v[154:157], v[206:209], v[92:95]
	v_mfma_f32_16x16x32_bf16 v[88:91], v[162:165], v[206:209], v[88:91]
	v_mfma_f32_16x16x32_bf16 v[76:79], v[154:157], v[214:217], v[76:79]
	v_mfma_f32_16x16x32_bf16 v[72:75], v[162:165], v[214:217], v[72:75]
	s_setprio 0
	s_setprio 1
	v_mfma_f32_16x16x32_bf16 v[116:119], v[166:169], v[182:185], v[116:119]
	v_mfma_f32_16x16x32_bf16 v[112:115], v[174:177], v[182:185], v[112:115]
	v_mfma_f32_16x16x32_bf16 v[100:103], v[166:169], v[190:193], v[100:103]
	v_mfma_f32_16x16x32_bf16 v[96:99], v[174:177], v[190:193], v[96:99]
	v_mfma_f32_16x16x32_bf16 v[84:87], v[166:169], v[202:205], v[84:87]
	v_mfma_f32_16x16x32_bf16 v[80:83], v[174:177], v[202:205], v[80:83]
	v_mfma_f32_16x16x32_bf16 v[68:71], v[166:169], v[210:213], v[68:71]
	v_mfma_f32_16x16x32_bf16 v[64:67], v[174:177], v[210:213], v[64:67]
	v_mfma_f32_16x16x32_bf16 v[116:119], v[170:173], v[186:189], v[116:119]
	v_mfma_f32_16x16x32_bf16 v[112:115], v[178:181], v[186:189], v[112:115]
	v_mfma_f32_16x16x32_bf16 v[100:103], v[170:173], v[198:201], v[100:103]
	v_mfma_f32_16x16x32_bf16 v[96:99], v[178:181], v[198:201], v[96:99]
	v_mfma_f32_16x16x32_bf16 v[84:87], v[170:173], v[206:209], v[84:87]
	v_mfma_f32_16x16x32_bf16 v[80:83], v[178:181], v[206:209], v[80:83]
	v_mfma_f32_16x16x32_bf16 v[68:71], v[170:173], v[214:217], v[68:71]
	v_mfma_f32_16x16x32_bf16 v[64:67], v[178:181], v[214:217], v[64:67]
	s_setprio 0
	s_barrier
	s_add_i32 s51, s42, s30
	v_lshl_add_u64 v[194:195], s[26:27], 0, v[130:131]
	s_mov_b32 m0, s51
	ds_read_b128 v[182:185], v153 offset:16384
	ds_read_b128 v[186:189], v153 offset:17408
	ds_read_b128 v[190:193], v153 offset:18432
	ds_read_b128 v[198:201], v153 offset:19456
	ds_read_b128 v[202:205], v153 offset:20480
	ds_read_b128 v[206:209], v153 offset:21504
	ds_read_b128 v[210:213], v153 offset:22528
	ds_read_b128 v[214:217], v153 offset:23552
	global_load_lds_dwordx4 v[194:195], off
	s_add_i32 m0, s51, 0x2000
	s_add_u32 s52, s26, 0x40000
	v_lshl_add_u64 v[218:219], s[26:27], 0, v[134:135]
	s_addc_u32 s53, s27, 0
	s_add_i32 s51, s43, s30
	global_load_lds_dwordx4 v[218:219], off
	v_lshl_add_u64 v[220:221], s[52:53], 0, v[130:131]
	s_mov_b32 m0, s51
	v_lshl_add_u64 v[222:223], s[28:29], 0, v[132:133]
	global_load_lds_dwordx4 v[220:221], off
	v_lshl_add_u64 v[220:221], s[52:53], 0, v[134:135]
	s_add_i32 m0, s51, 0x2000
	s_nop 0
	global_load_lds_dwordx4 v[220:221], off
	v_lshl_add_u64 v[220:221], s[28:29], 0, v[128:129]
	s_mov_b32 m0, s23
	s_nop 0
	global_load_lds_dwordx4 v[220:221], off
	s_mov_b32 m0, s34
	s_nop 0
	global_load_lds_dwordx4 v[222:223], off
	s_cmp_eq_u32 s50, s101
	s_cbranch_scc1 .Lrw0_r1
	s_waitcnt vmcnt(8)
.Lrw0_b1:
	s_waitcnt lgkmcnt(0)
	s_barrier
	s_setprio 1
	s_waitcnt lgkmcnt(0)
	v_mfma_f32_16x16x32_bf16 v[60:63], v[144:147], v[182:185], v[60:63]
	v_mfma_f32_16x16x32_bf16 v[56:59], v[158:161], v[182:185], v[56:59]
	v_mfma_f32_16x16x32_bf16 v[44:47], v[144:147], v[190:193], v[44:47]
	v_mfma_f32_16x16x32_bf16 v[40:43], v[158:161], v[190:193], v[40:43]
	v_mfma_f32_16x16x32_bf16 v[28:31], v[144:147], v[202:205], v[28:31]
	v_mfma_f32_16x16x32_bf16 v[24:27], v[158:161], v[202:205], v[24:27]
	v_mfma_f32_16x16x32_bf16 v[12:15], v[144:147], v[210:213], v[12:15]
	v_mfma_f32_16x16x32_bf16 v[8:11], v[158:161], v[210:213], v[8:11]
	v_mfma_f32_16x16x32_bf16 v[60:63], v[154:157], v[186:189], v[60:63]
	v_mfma_f32_16x16x32_bf16 v[56:59], v[162:165], v[186:189], v[56:59]
	v_mfma_f32_16x16x32_bf16 v[44:47], v[154:157], v[198:201], v[44:47]
	v_mfma_f32_16x16x32_bf16 v[40:43], v[162:165], v[198:201], v[40:43]
	v_mfma_f32_16x16x32_bf16 v[28:31], v[154:157], v[206:209], v[28:31]
	v_mfma_f32_16x16x32_bf16 v[24:27], v[162:165], v[206:209], v[24:27]
	v_mfma_f32_16x16x32_bf16 v[12:15], v[154:157], v[214:217], v[12:15]
	v_mfma_f32_16x16x32_bf16 v[8:11], v[162:165], v[214:217], v[8:11]
	s_setprio 0
	s_setprio 1
	v_mfma_f32_16x16x32_bf16 v[52:55], v[166:169], v[182:185], v[52:55]
	v_mfma_f32_16x16x32_bf16 v[48:51], v[174:177], v[182:185], v[48:51]
	v_mfma_f32_16x16x32_bf16 v[36:39], v[166:169], v[190:193], v[36:39]
	v_mfma_f32_16x16x32_bf16 v[32:35], v[174:177], v[190:193], v[32:35]
	v_mfma_f32_16x16x32_bf16 v[20:23], v[166:169], v[202:205], v[20:23]
	v_mfma_f32_16x16x32_bf16 v[16:19], v[174:177], v[202:205], v[16:19]
	v_mfma_f32_16x16x32_bf16 v[4:7], v[166:169], v[210:213], v[4:7]
	v_mfma_f32_16x16x32_bf16 v[0:3], v[174:177], v[210:213], v[0:3]
	v_mfma_f32_16x16x32_bf16 v[52:55], v[170:173], v[186:189], v[52:55]
	v_mfma_f32_16x16x32_bf16 v[48:51], v[178:181], v[186:189], v[48:51]
	v_mfma_f32_16x16x32_bf16 v[36:39], v[170:173], v[198:201], v[36:39]
	v_mfma_f32_16x16x32_bf16 v[32:35], v[178:181], v[198:201], v[32:35]
	v_mfma_f32_16x16x32_bf16 v[20:23], v[170:173], v[206:209], v[20:23]
	v_mfma_f32_16x16x32_bf16 v[16:19], v[178:181], v[206:209], v[16:19]
	v_mfma_f32_16x16x32_bf16 v[4:7], v[170:173], v[214:217], v[4:7]
	v_mfma_f32_16x16x32_bf16 v[0:3], v[178:181], v[214:217], v[0:3]
	s_setprio 0
	s_barrier
; #define PG8_STAGE(bufoff, gbase, voff) do { _Pragma("unroll") for (int _i = 0; _i < 2; ++_i) \
;         __builtin_amdgcn_global_load_lds((const unsigned*)((const char*)(gbase) + (voff)[_i]), (PG8_LAS unsigned*)(lds + (bufoff) + ldsw + _i * 8192), 16, 0, 0); } while (0)
; #define PG8_LDA(dst, b, h) do { _Pragma("unroll") for (int m = 0; m < 4; ++m) _Pragma("unroll") for (int k = 0; k < 2; ++k) dst[m][k] = *(const PG8_LAS bf16x8*)(lds + PG8_SA(b, h) + aoff + m * 2048 + k * 1024); } while (0)
; #define PG8_LDB(dst, b, h) do { _Pragma("unroll") for (int n = 0; n < 2; ++n) _Pragma("unroll") for (int k = 0; k < 2; ++k) dst[n][k] = *(const PG8_LAS bf16x8*)(lds + PG8_SB(b, h) + boff + n * 2048 + k * 1024); } while (0)
; #define PG8_MMA(ai, bj, At, Bt) do { __builtin_amdgcn_s_setprio(1); _Pragma("unroll") for (int m = 0; m < 4; ++m) _Pragma("unroll") for (int n = 0; n < 2; ++n) _Pragma("unroll") for (int k = 0; k < 2; ++k) \
;         acc[ai][bj][m][n] = __builtin_amdgcn_mfma_f32_16x16x32_bf16(Bt[n][k], At[m][k], acc[ai][bj][m][n], 0, 0, 0); __builtin_amdgcn_s_setprio(0); } while (0)
; #define PG8_WAIT_V(n) asm volatile("s_waitcnt vmcnt(" #n ")" ::: "memory")
; #define PG8_WAIT_L(n) asm volatile("s_waitcnt lgkmcnt(" #n ")" ::: "memory")
; #define PG8_BAR __builtin_amdgcn_s_barrier()
; #define PG8_SCHED __builtin_amdgcn_sched_barrier(0)
; template <class Epi, class Sched, bool ALIGN_EPI = false, bool SP2 = false>
; __device__ __forceinline__ void gemm_phase(PG8_LAS unsigned char* lds, const Gemm g, const Sched& S, const Epi& E) {
;     ...
;             PG8_LDB(B0, 1, 0); PG8_LDB(B1, 1, 1); PG8_SCHED; PG8_LDA(At, 1, 0); PG8_STAGE(PG8_SA(0, 1), a2 + hstep, voffA);
;             PG8_WAIT_V(8); PG8_WAIT_L(0); PG8_BAR; PG8_MMA(0, 0, At, B0); PG8_MMA(0, 1, At, B1); PG8_BAR; PG8_SCHED;
	s_add_i32 s51, 0, 0x18000
	s_add_i32 s52, 0, 0x1c000
	v_add_u32_e32 v162, s51, v149
	v_add_u32_e32 v178, s52, v149
	ds_read_b128 v[144:147], v162
	ds_read_b128 v[154:157], v162 offset:1024
	ds_read_b128 v[158:161], v162 offset:2048
	ds_read_b128 v[162:165], v162 offset:3072
	ds_read_b128 v[166:169], v178
	ds_read_b128 v[170:173], v178 offset:1024
	ds_read_b128 v[174:177], v178 offset:2048
	ds_read_b128 v[178:181], v178 offset:3072
	s_add_u32 s28, s28, 0x40000
	s_addc_u32 s29, s29, 0
	s_mov_b32 m0, s35
	v_lshl_add_u64 v[224:225], s[28:29], 0, v[128:129]
	ds_read_b128 v[182:185], v153 offset:32768
	ds_read_b128 v[186:189], v153 offset:33792
	ds_read_b128 v[190:193], v153 offset:34816
	ds_read_b128 v[198:201], v153 offset:35840
	ds_read_b128 v[202:205], v153 offset:36864
	ds_read_b128 v[206:209], v153 offset:37888
	ds_read_b128 v[210:213], v153 offset:38912
	ds_read_b128 v[214:217], v153 offset:39936
	global_load_lds_dwordx4 v[224:225], off
	v_lshl_add_u64 v[224:225], s[28:29], 0, v[132:133]
	s_mov_b32 m0, s36
	s_nop 0
	global_load_lds_dwordx4 v[224:225], off
	s_waitcnt vmcnt(8)
	s_waitcnt lgkmcnt(0)
	s_barrier
	s_setprio 1
	s_waitcnt lgkmcnt(0)
	v_mfma_f32_16x16x32_bf16 v[124:127], v[144:147], v[182:185], v[124:127]
	v_mfma_f32_16x16x32_bf16 v[120:123], v[158:161], v[182:185], v[120:123]
	v_mfma_f32_16x16x32_bf16 v[108:111], v[144:147], v[190:193], v[108:111]
	v_mfma_f32_16x16x32_bf16 v[104:107], v[158:161], v[190:193], v[104:107]
	v_mfma_f32_16x16x32_bf16 v[92:95], v[144:147], v[202:205], v[92:95]
	v_mfma_f32_16x16x32_bf16 v[88:91], v[158:161], v[202:205], v[88:91]
	v_mfma_f32_16x16x32_bf16 v[76:79], v[144:147], v[210:213], v[76:79]
	v_mfma_f32_16x16x32_bf16 v[72:75], v[158:161], v[210:213], v[72:75]
	v_mfma_f32_16x16x32_bf16 v[124:127], v[154:157], v[186:189], v[124:127]
	v_mfma_f32_16x16x32_bf16 v[120:123], v[162:165], v[186:189], v[120:123]
	v_mfma_f32_16x16x32_bf16 v[108:111], v[154:157], v[198:201], v[108:111]
	v_mfma_f32_16x16x32_bf16 v[104:107], v[162:165], v[198:201], v[104:107]
	v_mfma_f32_16x16x32_bf16 v[92:95], v[154:157], v[206:209], v[92:95]
	v_mfma_f32_16x16x32_bf16 v[88:91], v[162:165], v[206:209], v[88:91]
	v_mfma_f32_16x16x32_bf16 v[76:79], v[154:157], v[214:217], v[76:79]
	v_mfma_f32_16x16x32_bf16 v[72:75], v[162:165], v[214:217], v[72:75]
	s_setprio 0
	s_setprio 1
	v_mfma_f32_16x16x32_bf16 v[116:119], v[166:169], v[182:185], v[116:119]
	v_mfma_f32_16x16x32_bf16 v[112:115], v[174:177], v[182:185], v[112:115]
	v_mfma_f32_16x16x32_bf16 v[100:103], v[166:169], v[190:193], v[100:103]
	v_mfma_f32_16x16x32_bf16 v[96:99], v[174:177], v[190:193], v[96:99]
	v_mfma_f32_16x16x32_bf16 v[84:87], v[166:169], v[202:205], v[84:87]
	v_mfma_f32_16x16x32_bf16 v[80:83], v[174:177], v[202:205], v[80:83]
	v_mfma_f32_16x16x32_bf16 v[68:71], v[166:169], v[210:213], v[68:71]
	v_mfma_f32_16x16x32_bf16 v[64:67], v[174:177], v[210:213], v[64:67]
	v_mfma_f32_16x16x32_bf16 v[116:119], v[170:173], v[186:189], v[116:119]
	v_mfma_f32_16x16x32_bf16 v[112:115], v[178:181], v[186:189], v[112:115]
	v_mfma_f32_16x16x32_bf16 v[100:103], v[170:173], v[198:201], v[100:103]
	v_mfma_f32_16x16x32_bf16 v[96:99], v[178:181], v[198:201], v[96:99]
	v_mfma_f32_16x16x32_bf16 v[84:87], v[170:173], v[206:209], v[84:87]
	v_mfma_f32_16x16x32_bf16 v[80:83], v[178:181], v[206:209], v[80:83]
	v_mfma_f32_16x16x32_bf16 v[68:71], v[170:173], v[214:217], v[68:71]
	v_mfma_f32_16x16x32_bf16 v[64:67], v[178:181], v[214:217], v[64:67]
	s_setprio 0
	s_barrier
; #define PG8_STAGE(bufoff, gbase, voff) do { _Pragma("unroll") for (int _i = 0; _i < 2; ++_i) \
;         __builtin_amdgcn_global_load_lds((const unsigned*)((const char*)(gbase) + (voff)[_i]), (PG8_LAS unsigned*)(lds + (bufoff) + ldsw + _i * 8192), 16, 0, 0); } while (0)
; #define PG8_LDA(dst, b, h) do { _Pragma("unroll") for (int m = 0; m < 4; ++m) _Pragma("unroll") for (int k = 0; k < 2; ++k) dst[m][k] = *(const PG8_LAS bf16x8*)(lds + PG8_SA(b, h) + aoff + m * 2048 + k * 1024); } while (0)
; #define PG8_MMA(ai, bj, At, Bt) do { __builtin_amdgcn_s_setprio(1); _Pragma("unroll") for (int m = 0; m < 4; ++m) _Pragma("unroll") for (int n = 0; n < 2; ++n) _Pragma("unroll") for (int k = 0; k < 2; ++k) \
;         acc[ai][bj][m][n] = __builtin_amdgcn_mfma_f32_16x16x32_bf16(Bt[n][k], At[m][k], acc[ai][bj][m][n], 0, 0, 0); __builtin_amdgcn_s_setprio(0); } while (0)
; #define PG8_WAIT_V(n) asm volatile("s_waitcnt vmcnt(" #n ")" ::: "memory")
; #define PG8_WAIT_L(n) asm volatile("s_waitcnt lgkmcnt(" #n ")" ::: "memory")
; #define PG8_BAR __builtin_amdgcn_s_barrier()
; #define PG8_SCHED __builtin_amdgcn_sched_barrier(0)
; template <class Epi, class Sched, bool ALIGN_EPI = false, bool SP2 = false>
; __device__ __forceinline__ void gemm_phase(PG8_LAS unsigned char* lds, const Gemm g, const Sched& S, const Epi& E) {
;     ...
;             PG8_LDA(At, 1, 1); PG8_STAGE(PG8_SB(1, 0), b3, voffB); PG8_STAGE(PG8_SB(1, 1), b3 + hstep, voffB); PG8_STAGE(PG8_SA(1, 0), a3, voffA);
;             PG8_WAIT_V(8); PG8_WAIT_L(0); PG8_BAR; PG8_MMA(1, 0, At, B0); PG8_MMA(1, 1, At, B1); PG8_BAR; PG8_SCHED;
	s_add_i32 s28, s51, s30
	v_lshl_add_u64 v[194:195], v[194:195], 0, s[10:11]
	s_mov_b32 m0, s28
	ds_read_b128 v[182:185], v153 offset:49152
	ds_read_b128 v[186:189], v153 offset:50176
	ds_read_b128 v[190:193], v153 offset:51200
	ds_read_b128 v[198:201], v153 offset:52224
	ds_read_b128 v[202:205], v153 offset:53248
	ds_read_b128 v[206:209], v153 offset:54272
	ds_read_b128 v[210:213], v153 offset:55296
	ds_read_b128 v[214:217], v153 offset:56320
	global_load_lds_dwordx4 v[194:195], off
	s_add_i32 m0, s28, 0x2000
	s_add_u32 s26, s26, 0x40080
	v_lshl_add_u64 v[194:195], v[218:219], 0, s[10:11]
	s_addc_u32 s27, s27, 0
	s_add_i32 s28, s52, s30
	global_load_lds_dwordx4 v[194:195], off
	v_lshl_add_u64 v[194:195], s[26:27], 0, v[130:131]
	s_mov_b32 m0, s28
	s_nop 0
	global_load_lds_dwordx4 v[194:195], off
	v_lshl_add_u64 v[194:195], s[26:27], 0, v[134:135]
	s_add_i32 m0, s28, 0x2000
	s_nop 0
	global_load_lds_dwordx4 v[194:195], off
	v_lshl_add_u64 v[194:195], v[220:221], 0, s[10:11]
	s_mov_b32 m0, s39
	s_nop 0
	global_load_lds_dwordx4 v[194:195], off
	v_lshl_add_u64 v[194:195], v[222:223], 0, s[10:11]
	s_mov_b32 m0, s40
	s_nop 0
	global_load_lds_dwordx4 v[194:195], off
	s_waitcnt vmcnt(8)
	s_waitcnt lgkmcnt(0)
	s_barrier
	s_setprio 1
	s_waitcnt lgkmcnt(0)
	v_mfma_f32_16x16x32_bf16 v[60:63], v[144:147], v[182:185], v[60:63]
	v_mfma_f32_16x16x32_bf16 v[56:59], v[158:161], v[182:185], v[56:59]
	v_mfma_f32_16x16x32_bf16 v[44:47], v[144:147], v[190:193], v[44:47]
	v_mfma_f32_16x16x32_bf16 v[40:43], v[158:161], v[190:193], v[40:43]
	v_mfma_f32_16x16x32_bf16 v[28:31], v[144:147], v[202:205], v[28:31]
	v_mfma_f32_16x16x32_bf16 v[24:27], v[158:161], v[202:205], v[24:27]
	v_mfma_f32_16x16x32_bf16 v[12:15], v[144:147], v[210:213], v[12:15]
	v_mfma_f32_16x16x32_bf16 v[8:11], v[158:161], v[210:213], v[8:11]
	v_mfma_f32_16x16x32_bf16 v[60:63], v[154:157], v[186:189], v[60:63]
	v_mfma_f32_16x16x32_bf16 v[56:59], v[162:165], v[186:189], v[56:59]
	v_mfma_f32_16x16x32_bf16 v[44:47], v[154:157], v[198:201], v[44:47]
	v_mfma_f32_16x16x32_bf16 v[40:43], v[162:165], v[198:201], v[40:43]
	v_mfma_f32_16x16x32_bf16 v[28:31], v[154:157], v[206:209], v[28:31]
	v_mfma_f32_16x16x32_bf16 v[24:27], v[162:165], v[206:209], v[24:27]
	v_mfma_f32_16x16x32_bf16 v[12:15], v[154:157], v[214:217], v[12:15]
	v_mfma_f32_16x16x32_bf16 v[8:11], v[162:165], v[214:217], v[8:11]
	s_setprio 0
	s_setprio 1
	v_mfma_f32_16x16x32_bf16 v[52:55], v[166:169], v[182:185], v[52:55]
	v_mfma_f32_16x16x32_bf16 v[48:51], v[174:177], v[182:185], v[48:51]
	v_mfma_f32_16x16x32_bf16 v[36:39], v[166:169], v[190:193], v[36:39]
	v_mfma_f32_16x16x32_bf16 v[32:35], v[174:177], v[190:193], v[32:35]
	v_mfma_f32_16x16x32_bf16 v[20:23], v[166:169], v[202:205], v[20:23]
	v_mfma_f32_16x16x32_bf16 v[16:19], v[174:177], v[202:205], v[16:19]
	v_mfma_f32_16x16x32_bf16 v[4:7], v[166:169], v[210:213], v[4:7]
	v_mfma_f32_16x16x32_bf16 v[0:3], v[174:177], v[210:213], v[0:3]
	v_mfma_f32_16x16x32_bf16 v[52:55], v[170:173], v[186:189], v[52:55]
	v_mfma_f32_16x16x32_bf16 v[48:51], v[178:181], v[186:189], v[48:51]
	v_mfma_f32_16x16x32_bf16 v[36:39], v[170:173], v[198:201], v[36:39]
	v_mfma_f32_16x16x32_bf16 v[32:35], v[178:181], v[198:201], v[32:35]
	v_mfma_f32_16x16x32_bf16 v[20:23], v[170:173], v[206:209], v[20:23]
	v_mfma_f32_16x16x32_bf16 v[16:19], v[178:181], v[206:209], v[16:19]
	v_mfma_f32_16x16x32_bf16 v[4:7], v[170:173], v[214:217], v[4:7]
	v_mfma_f32_16x16x32_bf16 v[0:3], v[178:181], v[214:217], v[0:3]
	s_setprio 0
	s_barrier
	s_add_i32 s50, s50, 2
	s_add_u32 s24, s24, 0x100
	s_addc_u32 s25, s25, 0
	s_add_u32 s48, s48, 0x100
	s_addc_u32 s49, s49, 0
	s_cmp_gt_u32 s50, 13
	s_cbranch_scc0 .LBB0_293
	s_branch .Lrw0_x
.Lrw0_r0:
	s_waitcnt vmcnt(16)
	s_branch .Lrw0_b0

; #define PG8_BAR __builtin_amdgcn_s_barrier()
; template <class Epi, class Sched, bool ALIGN_EPI = false, bool SP2 = false>
; __device__ __forceinline__ void gemm_phase(PG8_LAS unsigned char* lds, const Gemm g, const Sched& S, const Epi& E) {
;     ...
;         if constexpr (ALIGN_EPI) { if (wr == 0) PG8_BAR; }
;         if constexpr (!Epi::AFTER_DRAIN) { E(acc, cur, wr, wc, fr, fq); S.done(cur); }
.Lrw0_x:
	s_and_b64 vcc, exec, s[12:13]
	s_cbranch_vccz .LBB0_296
	s_barrier

; #define PG8_STAGE(bufoff, gbase, voff) do { _Pragma("unroll") for (int _i = 0; _i < 2; ++_i) \
;         __builtin_amdgcn_global_load_lds((const unsigned*)((const char*)(gbase) + (voff)[_i]), (PG8_LAS unsigned*)(lds + (bufoff) + ldsw + _i * 8192), 16, 0, 0); } while (0)
; #define PG8_LDA(dst, b, h) do { _Pragma("unroll") for (int m = 0; m < 4; ++m) _Pragma("unroll") for (int k = 0; k < 2; ++k) dst[m][k] = *(const PG8_LAS bf16x8*)(lds + PG8_SA(b, h) + aoff + m * 2048 + k * 1024); } while (0)
; #define PG8_LDB(dst, b, h) do { _Pragma("unroll") for (int n = 0; n < 2; ++n) _Pragma("unroll") for (int k = 0; k < 2; ++k) dst[n][k] = *(const PG8_LAS bf16x8*)(lds + PG8_SB(b, h) + boff + n * 2048 + k * 1024); } while (0)
; #define PG8_SCHED __builtin_amdgcn_sched_barrier(0)
;     __device__ __forceinline__ void operator()(const f32x4 (&acc)[2][2][4][2], const Unit& u, int wr, int wc, int fr, int fq) const {
;     ...
;                     const float rsc = rs ? rs[row0 + ai * HALF + m * 16] : 1.0f;
; template <class Epi, class Sched, bool ALIGN_EPI = false, bool SP2 = false>
; __device__ __forceinline__ void gemm_phase(PG8_LAS unsigned char* lds, const Gemm g, const Sched& S, const Epi& E) {
;     ...
;         const bool has_next = S.next(ui + 1, nxt);
;         const char* nA = has_next ? (const char*)g.A + (size_t)nxt.pm * tstep : cA; const char* nB = has_next ? (const char*)g.Bt + (size_t)nxt.pn * tstep : cB;
;         for (int t = 0; t < nt; t += 2) {
;             const bool last = (t == nt - 2);
;             const char* a1 = cA + (size_t)(t + 1) * kstep;
;             const char* a2 = last ? nA : cA + (size_t)(t + 2) * kstep; const char* b2 = last ? nB : cB + (size_t)(t + 2) * kstep;
;             const char* a3 = a2 + kstep; const char* b3 = b2 + kstep;
;             if (last && has_next) S.a_ready(nxt);
;             if constexpr (SP2) {
;             PG8_LDB(B0, 0, 0); PG8_LDB(B1, 0, 1); PG8_SCHED; PG8_LDA(At, 0, 0); PG8_STAGE(PG8_SA(1, 1), a1 + hstep, voffA);
.LBB0_524:
	s_ashr_i32 s23, s22, 31
	s_lshl_b64 s[24:25], s[22:23], 19
	s_add_u32 s24, s62, s24
	s_addc_u32 s25, s63, s25
	s_and_b64 s[26:27], s[0:1], exec
	s_cselect_b32 s3, s25, s31
	s_cselect_b32 s23, s24, s30
	s_ashr_i32 s21, s20, 31
	s_lshl_b64 s[26:27], s[20:21], 19
	s_add_u32 s26, s6, s26
	s_addc_u32 s27, s7, s27
	s_and_b64 s[36:37], s[0:1], exec
	s_cselect_b32 s21, s27, s35
	s_cselect_b32 s50, s26, s34
	s_add_u32 s30, s30, 0x40080
	s_addc_u32 s31, s31, 0
	s_add_u32 s51, s34, 0x100
	v_mov_b32_e32 v0, 0
	s_addc_u32 s52, s35, 0
	s_mov_b32 s53, -2
	v_mov_b32_e32 v1, v0
	v_mov_b32_e32 v2, v0
	v_mov_b32_e32 v3, v0
	v_mov_b32_e32 v4, v0
	v_mov_b32_e32 v5, v0
	v_mov_b32_e32 v6, v0
	v_mov_b32_e32 v7, v0
	v_mov_b32_e32 v8, v0
	v_mov_b32_e32 v9, v0
	v_mov_b32_e32 v10, v0
	v_mov_b32_e32 v11, v0
	v_mov_b32_e32 v12, v0
	v_mov_b32_e32 v13, v0
	v_mov_b32_e32 v14, v0
	v_mov_b32_e32 v15, v0
	v_mov_b32_e32 v16, v0
	v_mov_b32_e32 v17, v0
	v_mov_b32_e32 v18, v0
	v_mov_b32_e32 v19, v0
	v_mov_b32_e32 v20, v0
	v_mov_b32_e32 v21, v0
	v_mov_b32_e32 v22, v0
	v_mov_b32_e32 v23, v0
	v_mov_b32_e32 v24, v0
	v_mov_b32_e32 v25, v0
	v_mov_b32_e32 v26, v0
	v_mov_b32_e32 v27, v0
	v_mov_b32_e32 v28, v0
	v_mov_b32_e32 v29, v0
	v_mov_b32_e32 v30, v0
	v_mov_b32_e32 v31, v0
	v_mov_b32_e32 v60, v0
	v_mov_b32_e32 v61, v0
	v_mov_b32_e32 v62, v0
	v_mov_b32_e32 v63, v0
	v_mov_b32_e32 v68, v0
	v_mov_b32_e32 v69, v0
	v_mov_b32_e32 v70, v0
	v_mov_b32_e32 v71, v0
	v_mov_b32_e32 v72, v0
	v_mov_b32_e32 v73, v0
	v_mov_b32_e32 v74, v0
	v_mov_b32_e32 v75, v0
	v_mov_b32_e32 v76, v0
	v_mov_b32_e32 v77, v0
	v_mov_b32_e32 v78, v0
	v_mov_b32_e32 v79, v0
	v_mov_b32_e32 v80, v0
	v_mov_b32_e32 v81, v0
	v_mov_b32_e32 v82, v0
	v_mov_b32_e32 v83, v0
	v_mov_b32_e32 v84, v0
	v_mov_b32_e32 v85, v0
	v_mov_b32_e32 v86, v0
	v_mov_b32_e32 v87, v0
	v_mov_b32_e32 v88, v0
	v_mov_b32_e32 v89, v0
	v_mov_b32_e32 v90, v0
	v_mov_b32_e32 v91, v0
	v_mov_b32_e32 v92, v0
	v_mov_b32_e32 v93, v0
	v_mov_b32_e32 v94, v0
	v_mov_b32_e32 v95, v0
	v_mov_b32_e32 v32, v0
	v_mov_b32_e32 v33, v0
	v_mov_b32_e32 v34, v0
	v_mov_b32_e32 v35, v0
	v_mov_b32_e32 v36, v0
	v_mov_b32_e32 v37, v0
	v_mov_b32_e32 v38, v0
	v_mov_b32_e32 v39, v0
	v_mov_b32_e32 v40, v0
	v_mov_b32_e32 v41, v0
	v_mov_b32_e32 v42, v0
	v_mov_b32_e32 v43, v0
	v_mov_b32_e32 v44, v0
	v_mov_b32_e32 v45, v0
	v_mov_b32_e32 v46, v0
	v_mov_b32_e32 v47, v0
	v_mov_b32_e32 v48, v0
	v_mov_b32_e32 v49, v0
	v_mov_b32_e32 v50, v0
	v_mov_b32_e32 v51, v0
	v_mov_b32_e32 v52, v0
	v_mov_b32_e32 v53, v0
	v_mov_b32_e32 v54, v0
	v_mov_b32_e32 v55, v0
	v_mov_b32_e32 v56, v0
	v_mov_b32_e32 v57, v0
	v_mov_b32_e32 v58, v0
	v_mov_b32_e32 v59, v0
	v_mov_b32_e32 v64, v0
	v_mov_b32_e32 v65, v0
	v_mov_b32_e32 v66, v0
	v_mov_b32_e32 v67, v0
	v_mov_b32_e32 v96, v0
	v_mov_b32_e32 v97, v0
	v_mov_b32_e32 v98, v0
	v_mov_b32_e32 v99, v0
	v_mov_b32_e32 v100, v0
	v_mov_b32_e32 v101, v0
	v_mov_b32_e32 v102, v0
	v_mov_b32_e32 v103, v0
	v_mov_b32_e32 v104, v0
	v_mov_b32_e32 v105, v0
	v_mov_b32_e32 v106, v0
	v_mov_b32_e32 v107, v0
	v_mov_b32_e32 v108, v0
	v_mov_b32_e32 v109, v0
	v_mov_b32_e32 v110, v0
	v_mov_b32_e32 v111, v0
	v_mov_b32_e32 v112, v0
	v_mov_b32_e32 v113, v0
	v_mov_b32_e32 v114, v0
	v_mov_b32_e32 v115, v0
	v_mov_b32_e32 v116, v0
	v_mov_b32_e32 v117, v0
	v_mov_b32_e32 v118, v0
	v_mov_b32_e32 v119, v0
	v_mov_b32_e32 v120, v0
	v_mov_b32_e32 v121, v0
	v_mov_b32_e32 v122, v0
	v_mov_b32_e32 v123, v0
	v_mov_b32_e32 v124, v0
	v_mov_b32_e32 v125, v0
	v_mov_b32_e32 v126, v0
	v_mov_b32_e32 v127, v0
	v_lshl_add_u32 v144, s2, 8, v153
	v_ashrrev_i32_e32 v145, 31, v144
	v_lshl_add_u64 v[146:147], v[144:145], 2, s[4:5]
	global_load_dword v230, v[146:147], off
	global_load_dword v232, v[146:147], off offset:64
	global_load_dword v234, v[146:147], off offset:128
	global_load_dword v236, v[146:147], off offset:192
	global_load_dword v238, v[146:147], off offset:512
	global_load_dword v240, v[146:147], off offset:576
	global_load_dword v242, v[146:147], off offset:640
	global_load_dword v244, v[146:147], off offset:704
	s_cmp_eq_u32 s41, 1
	s_cselect_b32 s101, 0x7fffffff, -2
.LBB0_525:
	ds_read_b128 v[144:147], v157
	ds_read_b128 v[148:151], v157 offset:1024
	ds_read_b128 v[162:165], v157 offset:2048
	ds_read_b128 v[166:169], v157 offset:3072
	ds_read_b128 v[170:173], v158
	ds_read_b128 v[174:177], v158 offset:1024
	ds_read_b128 v[178:181], v158 offset:2048
	ds_read_b128 v[182:185], v158 offset:3072
	s_add_u32 s34, s30, 0xfffc0080
	s_addc_u32 s35, s31, -1
	s_cmp_eq_u32 s53, 12
	s_cselect_b32 s37, s3, s35
	s_cselect_b32 s36, s23, s34
	s_cselect_b32 s35, s21, s52
	s_cselect_b32 s34, s50, s51
	v_lshl_add_u64 v[194:195], s[30:31], 0, v[136:137]
	s_add_i32 m0, s29, 0xc000
	ds_read_b128 v[186:189], v159
	ds_read_b128 v[190:193], v159 offset:1024
	ds_read_b128 v[198:201], v159 offset:2048
	ds_read_b128 v[202:205], v159 offset:3072
	ds_read_b128 v[206:209], v159 offset:4096
	ds_read_b128 v[210:213], v159 offset:5120
	ds_read_b128 v[214:217], v159 offset:6144
	ds_read_b128 v[218:221], v159 offset:7168
	global_load_lds_dwordx4 v[194:195], off
	v_lshl_add_u64 v[194:195], s[30:31], 0, v[138:139]
	s_add_i32 m0, s29, 0xe000
	s_nop 0
	global_load_lds_dwordx4 v[194:195], off
	s_cmp_eq_u32 s53, s101
	s_cbranch_scc1 .Lrw1_r0
	s_waitcnt vmcnt(8)
; #define PG8_STAGE(bufoff, gbase, voff) do { _Pragma("unroll") for (int _i = 0; _i < 2; ++_i) \
;         __builtin_amdgcn_global_load_lds((const unsigned*)((const char*)(gbase) + (voff)[_i]), (PG8_LAS unsigned*)(lds + (bufoff) + ldsw + _i * 8192), 16, 0, 0); } while (0)
; #define PG8_LDA(dst, b, h) do { _Pragma("unroll") for (int m = 0; m < 4; ++m) _Pragma("unroll") for (int k = 0; k < 2; ++k) dst[m][k] = *(const PG8_LAS bf16x8*)(lds + PG8_SA(b, h) + aoff + m * 2048 + k * 1024); } while (0)
; #define PG8_LDB(dst, b, h) do { _Pragma("unroll") for (int n = 0; n < 2; ++n) _Pragma("unroll") for (int k = 0; k < 2; ++k) dst[n][k] = *(const PG8_LAS bf16x8*)(lds + PG8_SB(b, h) + boff + n * 2048 + k * 1024); } while (0)
; #define PG8_MMA(ai, bj, At, Bt) do { __builtin_amdgcn_s_setprio(1); _Pragma("unroll") for (int m = 0; m < 4; ++m) _Pragma("unroll") for (int n = 0; n < 2; ++n) _Pragma("unroll") for (int k = 0; k < 2; ++k) \
;         acc[ai][bj][m][n] = __builtin_amdgcn_mfma_f32_16x16x32_bf16(Bt[n][k], At[m][k], acc[ai][bj][m][n], 0, 0, 0); __builtin_amdgcn_s_setprio(0); } while (0)
; #define PG8_WAIT_V(n) asm volatile("s_waitcnt vmcnt(" #n ")" ::: "memory")
; #define PG8_WAIT_L(n) asm volatile("s_waitcnt lgkmcnt(" #n ")" ::: "memory")
; #define PG8_BAR __builtin_amdgcn_s_barrier()
; #define PG8_SCHED __builtin_amdgcn_sched_barrier(0)
; template <class Epi, class Sched, bool ALIGN_EPI = false, bool SP2 = false>
; __device__ __forceinline__ void gemm_phase(PG8_LAS unsigned char* lds, const Gemm g, const Sched& S, const Epi& E) {
;     ...
;             PG8_LDB(B0, 0, 0); PG8_LDB(B1, 0, 1); PG8_SCHED; PG8_LDA(At, 0, 0); PG8_STAGE(PG8_SA(1, 1), a1 + hstep, voffA);
;             PG8_WAIT_V(8); PG8_WAIT_L(0); PG8_BAR; PG8_MMA(0, 0, At, B0); PG8_MMA(0, 1, At, B1); PG8_BAR; PG8_SCHED;
;             PG8_LDA(At, 0, 1); PG8_STAGE(PG8_SB(0, 0), b2, voffB); PG8_STAGE(PG8_SB(0, 1), b2 + hstep, voffB); PG8_STAGE(PG8_SA(0, 0), a2, voffA);
;             PG8_WAIT_V(8); PG8_WAIT_L(0); PG8_BAR; PG8_MMA(1, 0, At, B0); PG8_MMA(1, 1, At, B1); PG8_BAR; PG8_SCHED;
.Lrw1_b0:
	s_waitcnt lgkmcnt(0)
	s_barrier
	s_setprio 1
	s_waitcnt lgkmcnt(0)
	v_mfma_f32_16x16x32_bf16 v[124:127], v[144:147], v[186:189], v[124:127]
	v_mfma_f32_16x16x32_bf16 v[120:123], v[162:165], v[186:189], v[120:123]
	v_mfma_f32_16x16x32_bf16 v[116:119], v[144:147], v[198:201], v[116:119]
	v_mfma_f32_16x16x32_bf16 v[112:115], v[162:165], v[198:201], v[112:115]
	v_mfma_f32_16x16x32_bf16 v[108:111], v[144:147], v[206:209], v[108:111]
	v_mfma_f32_16x16x32_bf16 v[104:107], v[162:165], v[206:209], v[104:107]
	v_mfma_f32_16x16x32_bf16 v[100:103], v[144:147], v[214:217], v[100:103]
	v_mfma_f32_16x16x32_bf16 v[96:99], v[162:165], v[214:217], v[96:99]
	v_mfma_f32_16x16x32_bf16 v[124:127], v[148:151], v[190:193], v[124:127]
	v_mfma_f32_16x16x32_bf16 v[120:123], v[166:169], v[190:193], v[120:123]
	v_mfma_f32_16x16x32_bf16 v[116:119], v[148:151], v[202:205], v[116:119]
	v_mfma_f32_16x16x32_bf16 v[112:115], v[166:169], v[202:205], v[112:115]
	v_mfma_f32_16x16x32_bf16 v[108:111], v[148:151], v[210:213], v[108:111]
	v_mfma_f32_16x16x32_bf16 v[104:107], v[166:169], v[210:213], v[104:107]
	v_mfma_f32_16x16x32_bf16 v[100:103], v[148:151], v[218:221], v[100:103]
	v_mfma_f32_16x16x32_bf16 v[96:99], v[166:169], v[218:221], v[96:99]
	s_setprio 0
	s_setprio 1
	v_mfma_f32_16x16x32_bf16 v[64:67], v[170:173], v[186:189], v[64:67]
	v_mfma_f32_16x16x32_bf16 v[56:59], v[178:181], v[186:189], v[56:59]
	v_mfma_f32_16x16x32_bf16 v[52:55], v[170:173], v[198:201], v[52:55]
	v_mfma_f32_16x16x32_bf16 v[48:51], v[178:181], v[198:201], v[48:51]
	v_mfma_f32_16x16x32_bf16 v[44:47], v[170:173], v[206:209], v[44:47]
	v_mfma_f32_16x16x32_bf16 v[40:43], v[178:181], v[206:209], v[40:43]
	v_mfma_f32_16x16x32_bf16 v[36:39], v[170:173], v[214:217], v[36:39]
	v_mfma_f32_16x16x32_bf16 v[32:35], v[178:181], v[214:217], v[32:35]
	v_mfma_f32_16x16x32_bf16 v[64:67], v[174:177], v[190:193], v[64:67]
	v_mfma_f32_16x16x32_bf16 v[56:59], v[182:185], v[190:193], v[56:59]
	v_mfma_f32_16x16x32_bf16 v[52:55], v[174:177], v[202:205], v[52:55]
	v_mfma_f32_16x16x32_bf16 v[48:51], v[182:185], v[202:205], v[48:51]
	v_mfma_f32_16x16x32_bf16 v[44:47], v[174:177], v[210:213], v[44:47]
	v_mfma_f32_16x16x32_bf16 v[40:43], v[182:185], v[210:213], v[40:43]
	v_mfma_f32_16x16x32_bf16 v[36:39], v[174:177], v[218:221], v[36:39]
	v_mfma_f32_16x16x32_bf16 v[32:35], v[182:185], v[218:221], v[32:35]
	s_setprio 0
	s_barrier
	s_add_i32 s54, s47, s33
	v_lshl_add_u64 v[194:195], s[34:35], 0, v[130:131]
	s_mov_b32 m0, s54
	ds_read_b128 v[186:189], v159 offset:16384
	ds_read_b128 v[190:193], v159 offset:17408
	ds_read_b128 v[198:201], v159 offset:18432
	ds_read_b128 v[202:205], v159 offset:19456
	ds_read_b128 v[206:209], v159 offset:20480
	ds_read_b128 v[210:213], v159 offset:21504
	ds_read_b128 v[214:217], v159 offset:22528
	ds_read_b128 v[218:221], v159 offset:23552
	global_load_lds_dwordx4 v[194:195], off
	s_add_i32 m0, s54, 0x2000
	s_add_u32 s54, s34, 0x40000
	v_lshl_add_u64 v[222:223], s[34:35], 0, v[134:135]
	s_addc_u32 s55, s35, 0
	s_add_i32 s56, s48, s33
	global_load_lds_dwordx4 v[222:223], off
	v_lshl_add_u64 v[224:225], s[54:55], 0, v[130:131]
	s_mov_b32 m0, s56
	v_lshl_add_u64 v[226:227], s[36:37], 0, v[132:133]
	global_load_lds_dwordx4 v[224:225], off
	v_lshl_add_u64 v[224:225], s[54:55], 0, v[134:135]
	s_add_i32 m0, s56, 0x2000
	s_nop 0
	global_load_lds_dwordx4 v[224:225], off
	v_lshl_add_u64 v[224:225], s[36:37], 0, v[128:129]
	s_mov_b32 m0, s29
	s_nop 0
	global_load_lds_dwordx4 v[224:225], off
	s_mov_b32 m0, s38
	s_nop 0
	global_load_lds_dwordx4 v[226:227], off
	s_cmp_eq_u32 s53, s101
	s_cbranch_scc1 .Lrw1_r1
	s_waitcnt vmcnt(8)
.Lrw1_b1:
	s_waitcnt lgkmcnt(0)
	s_barrier
	s_setprio 1
	s_waitcnt lgkmcnt(0)
	v_mfma_f32_16x16x32_bf16 v[92:95], v[144:147], v[186:189], v[92:95]
	v_mfma_f32_16x16x32_bf16 v[88:91], v[162:165], v[186:189], v[88:91]
	v_mfma_f32_16x16x32_bf16 v[84:87], v[144:147], v[198:201], v[84:87]
	v_mfma_f32_16x16x32_bf16 v[80:83], v[162:165], v[198:201], v[80:83]
	v_mfma_f32_16x16x32_bf16 v[76:79], v[144:147], v[206:209], v[76:79]
	v_mfma_f32_16x16x32_bf16 v[72:75], v[162:165], v[206:209], v[72:75]
	v_mfma_f32_16x16x32_bf16 v[68:71], v[144:147], v[214:217], v[68:71]
	v_mfma_f32_16x16x32_bf16 v[60:63], v[162:165], v[214:217], v[60:63]
	v_mfma_f32_16x16x32_bf16 v[92:95], v[148:151], v[190:193], v[92:95]
	v_mfma_f32_16x16x32_bf16 v[88:91], v[166:169], v[190:193], v[88:91]
	v_mfma_f32_16x16x32_bf16 v[84:87], v[148:151], v[202:205], v[84:87]
	v_mfma_f32_16x16x32_bf16 v[80:83], v[166:169], v[202:205], v[80:83]
	v_mfma_f32_16x16x32_bf16 v[76:79], v[148:151], v[210:213], v[76:79]
	v_mfma_f32_16x16x32_bf16 v[72:75], v[166:169], v[210:213], v[72:75]
	v_mfma_f32_16x16x32_bf16 v[68:71], v[148:151], v[218:221], v[68:71]
	v_mfma_f32_16x16x32_bf16 v[60:63], v[166:169], v[218:221], v[60:63]
	s_setprio 0
	s_setprio 1
	v_mfma_f32_16x16x32_bf16 v[28:31], v[170:173], v[186:189], v[28:31]
	v_mfma_f32_16x16x32_bf16 v[24:27], v[178:181], v[186:189], v[24:27]
	v_mfma_f32_16x16x32_bf16 v[20:23], v[170:173], v[198:201], v[20:23]
	v_mfma_f32_16x16x32_bf16 v[16:19], v[178:181], v[198:201], v[16:19]
	v_mfma_f32_16x16x32_bf16 v[12:15], v[170:173], v[206:209], v[12:15]
	v_mfma_f32_16x16x32_bf16 v[8:11], v[178:181], v[206:209], v[8:11]
	v_mfma_f32_16x16x32_bf16 v[4:7], v[170:173], v[214:217], v[4:7]
	v_mfma_f32_16x16x32_bf16 v[0:3], v[178:181], v[214:217], v[0:3]
	v_mfma_f32_16x16x32_bf16 v[28:31], v[174:177], v[190:193], v[28:31]
	v_mfma_f32_16x16x32_bf16 v[24:27], v[182:185], v[190:193], v[24:27]
	v_mfma_f32_16x16x32_bf16 v[20:23], v[174:177], v[202:205], v[20:23]
	v_mfma_f32_16x16x32_bf16 v[16:19], v[182:185], v[202:205], v[16:19]
	v_mfma_f32_16x16x32_bf16 v[12:15], v[174:177], v[210:213], v[12:15]
	v_mfma_f32_16x16x32_bf16 v[8:11], v[182:185], v[210:213], v[8:11]
	v_mfma_f32_16x16x32_bf16 v[4:7], v[174:177], v[218:221], v[4:7]
	v_mfma_f32_16x16x32_bf16 v[0:3], v[182:185], v[218:221], v[0:3]
	s_setprio 0
	s_barrier
; #define PG8_STAGE(bufoff, gbase, voff) do { _Pragma("unroll") for (int _i = 0; _i < 2; ++_i) \
;         __builtin_amdgcn_global_load_lds((const unsigned*)((const char*)(gbase) + (voff)[_i]), (PG8_LAS unsigned*)(lds + (bufoff) + ldsw + _i * 8192), 16, 0, 0); } while (0)
; #define PG8_LDA(dst, b, h) do { _Pragma("unroll") for (int m = 0; m < 4; ++m) _Pragma("unroll") for (int k = 0; k < 2; ++k) dst[m][k] = *(const PG8_LAS bf16x8*)(lds + PG8_SA(b, h) + aoff + m * 2048 + k * 1024); } while (0)
; #define PG8_LDB(dst, b, h) do { _Pragma("unroll") for (int n = 0; n < 2; ++n) _Pragma("unroll") for (int k = 0; k < 2; ++k) dst[n][k] = *(const PG8_LAS bf16x8*)(lds + PG8_SB(b, h) + boff + n * 2048 + k * 1024); } while (0)
; #define PG8_MMA(ai, bj, At, Bt) do { __builtin_amdgcn_s_setprio(1); _Pragma("unroll") for (int m = 0; m < 4; ++m) _Pragma("unroll") for (int n = 0; n < 2; ++n) _Pragma("unroll") for (int k = 0; k < 2; ++k) \
;         acc[ai][bj][m][n] = __builtin_amdgcn_mfma_f32_16x16x32_bf16(Bt[n][k], At[m][k], acc[ai][bj][m][n], 0, 0, 0); __builtin_amdgcn_s_setprio(0); } while (0)
; #define PG8_WAIT_V(n) asm volatile("s_waitcnt vmcnt(" #n ")" ::: "memory")
; #define PG8_WAIT_L(n) asm volatile("s_waitcnt lgkmcnt(" #n ")" ::: "memory")
; #define PG8_BAR __builtin_amdgcn_s_barrier()
; #define PG8_SCHED __builtin_amdgcn_sched_barrier(0)
; template <class Epi, class Sched, bool ALIGN_EPI = false, bool SP2 = false>
; __device__ __forceinline__ void gemm_phase(PG8_LAS unsigned char* lds, const Gemm g, const Sched& S, const Epi& E) {
;     ...
;             PG8_LDB(B0, 1, 0); PG8_LDB(B1, 1, 1); PG8_SCHED; PG8_LDA(At, 1, 0); PG8_STAGE(PG8_SA(0, 1), a2 + hstep, voffA);
;             PG8_WAIT_V(8); PG8_WAIT_L(0); PG8_BAR; PG8_MMA(0, 0, At, B0); PG8_MMA(0, 1, At, B1); PG8_BAR; PG8_SCHED;
	s_add_i32 s54, 0, 0x18000
	v_add_u32_e32 v152, s54, v155
	s_add_i32 s55, 0, 0x1c000
	ds_read_b128 v[144:147], v152
	ds_read_b128 v[148:151], v152 offset:1024
	ds_read_b128 v[162:165], v152 offset:2048
	ds_read_b128 v[166:169], v152 offset:3072
	v_add_u32_e32 v152, s55, v155
	ds_read_b128 v[170:173], v152
	ds_read_b128 v[174:177], v152 offset:1024
	ds_read_b128 v[178:181], v152 offset:2048
	ds_read_b128 v[182:185], v152 offset:3072
	s_add_u32 s36, s36, 0x40000
	s_addc_u32 s37, s37, 0
	s_mov_b32 m0, s39
	v_lshl_add_u64 v[228:229], s[36:37], 0, v[128:129]
	ds_read_b128 v[186:189], v159 offset:32768
	ds_read_b128 v[190:193], v159 offset:33792
	ds_read_b128 v[198:201], v159 offset:34816
	ds_read_b128 v[202:205], v159 offset:35840
	ds_read_b128 v[206:209], v159 offset:36864
	ds_read_b128 v[210:213], v159 offset:37888
	ds_read_b128 v[214:217], v159 offset:38912
	ds_read_b128 v[218:221], v159 offset:39936
	global_load_lds_dwordx4 v[228:229], off
	v_lshl_add_u64 v[228:229], s[36:37], 0, v[132:133]
	s_mov_b32 m0, s40
	s_nop 0
	global_load_lds_dwordx4 v[228:229], off
	s_waitcnt vmcnt(8)
	s_waitcnt lgkmcnt(0)
	s_barrier
	s_setprio 1
	s_waitcnt lgkmcnt(0)
	v_mfma_f32_16x16x32_bf16 v[124:127], v[144:147], v[186:189], v[124:127]
	v_mfma_f32_16x16x32_bf16 v[120:123], v[162:165], v[186:189], v[120:123]
	v_mfma_f32_16x16x32_bf16 v[116:119], v[144:147], v[198:201], v[116:119]
	v_mfma_f32_16x16x32_bf16 v[112:115], v[162:165], v[198:201], v[112:115]
	v_mfma_f32_16x16x32_bf16 v[108:111], v[144:147], v[206:209], v[108:111]
	v_mfma_f32_16x16x32_bf16 v[104:107], v[162:165], v[206:209], v[104:107]
	v_mfma_f32_16x16x32_bf16 v[100:103], v[144:147], v[214:217], v[100:103]
	v_mfma_f32_16x16x32_bf16 v[96:99], v[162:165], v[214:217], v[96:99]
	v_mfma_f32_16x16x32_bf16 v[124:127], v[148:151], v[190:193], v[124:127]
	v_mfma_f32_16x16x32_bf16 v[120:123], v[166:169], v[190:193], v[120:123]
	v_mfma_f32_16x16x32_bf16 v[116:119], v[148:151], v[202:205], v[116:119]
	v_mfma_f32_16x16x32_bf16 v[112:115], v[166:169], v[202:205], v[112:115]
	v_mfma_f32_16x16x32_bf16 v[108:111], v[148:151], v[210:213], v[108:111]
	v_mfma_f32_16x16x32_bf16 v[104:107], v[166:169], v[210:213], v[104:107]
	v_mfma_f32_16x16x32_bf16 v[100:103], v[148:151], v[218:221], v[100:103]
	v_mfma_f32_16x16x32_bf16 v[96:99], v[166:169], v[218:221], v[96:99]
	s_setprio 0
	s_setprio 1
	v_mfma_f32_16x16x32_bf16 v[64:67], v[170:173], v[186:189], v[64:67]
	v_mfma_f32_16x16x32_bf16 v[56:59], v[178:181], v[186:189], v[56:59]
	v_mfma_f32_16x16x32_bf16 v[52:55], v[170:173], v[198:201], v[52:55]
	v_mfma_f32_16x16x32_bf16 v[48:51], v[178:181], v[198:201], v[48:51]
	v_mfma_f32_16x16x32_bf16 v[44:47], v[170:173], v[206:209], v[44:47]
	v_mfma_f32_16x16x32_bf16 v[40:43], v[178:181], v[206:209], v[40:43]
	v_mfma_f32_16x16x32_bf16 v[36:39], v[170:173], v[214:217], v[36:39]
	v_mfma_f32_16x16x32_bf16 v[32:35], v[178:181], v[214:217], v[32:35]
	v_mfma_f32_16x16x32_bf16 v[64:67], v[174:177], v[190:193], v[64:67]
	v_mfma_f32_16x16x32_bf16 v[56:59], v[182:185], v[190:193], v[56:59]
	v_mfma_f32_16x16x32_bf16 v[52:55], v[174:177], v[202:205], v[52:55]
	v_mfma_f32_16x16x32_bf16 v[48:51], v[182:185], v[202:205], v[48:51]
	v_mfma_f32_16x16x32_bf16 v[44:47], v[174:177], v[210:213], v[44:47]
	v_mfma_f32_16x16x32_bf16 v[40:43], v[182:185], v[210:213], v[40:43]
	v_mfma_f32_16x16x32_bf16 v[36:39], v[174:177], v[218:221], v[36:39]
	v_mfma_f32_16x16x32_bf16 v[32:35], v[182:185], v[218:221], v[32:35]
	s_setprio 0
	s_barrier
; #define PG8_STAGE(bufoff, gbase, voff) do { _Pragma("unroll") for (int _i = 0; _i < 2; ++_i) \
;         __builtin_amdgcn_global_load_lds((const unsigned*)((const char*)(gbase) + (voff)[_i]), (PG8_LAS unsigned*)(lds + (bufoff) + ldsw + _i * 8192), 16, 0, 0); } while (0)
; #define PG8_LDA(dst, b, h) do { _Pragma("unroll") for (int m = 0; m < 4; ++m) _Pragma("unroll") for (int k = 0; k < 2; ++k) dst[m][k] = *(const PG8_LAS bf16x8*)(lds + PG8_SA(b, h) + aoff + m * 2048 + k * 1024); } while (0)
; #define PG8_MMA(ai, bj, At, Bt) do { __builtin_amdgcn_s_setprio(1); _Pragma("unroll") for (int m = 0; m < 4; ++m) _Pragma("unroll") for (int n = 0; n < 2; ++n) _Pragma("unroll") for (int k = 0; k < 2; ++k) \
;         acc[ai][bj][m][n] = __builtin_amdgcn_mfma_f32_16x16x32_bf16(Bt[n][k], At[m][k], acc[ai][bj][m][n], 0, 0, 0); __builtin_amdgcn_s_setprio(0); } while (0)
; #define PG8_WAIT_V(n) asm volatile("s_waitcnt vmcnt(" #n ")" ::: "memory")
; #define PG8_WAIT_L(n) asm volatile("s_waitcnt lgkmcnt(" #n ")" ::: "memory")
; #define PG8_BAR __builtin_amdgcn_s_barrier()
; #define PG8_SCHED __builtin_amdgcn_sched_barrier(0)
; template <class Epi, class Sched, bool ALIGN_EPI = false, bool SP2 = false>
; __device__ __forceinline__ void gemm_phase(PG8_LAS unsigned char* lds, const Gemm g, const Sched& S, const Epi& E) {
;     ...
;             PG8_LDA(At, 1, 1); PG8_STAGE(PG8_SB(1, 0), b3, voffB); PG8_STAGE(PG8_SB(1, 1), b3 + hstep, voffB); PG8_STAGE(PG8_SA(1, 0), a3, voffA);
;             PG8_WAIT_V(8); PG8_WAIT_L(0); PG8_BAR; PG8_MMA(1, 0, At, B0); PG8_MMA(1, 1, At, B1); PG8_BAR; PG8_SCHED;
	s_add_i32 s36, s54, s33
	v_lshl_add_u64 v[194:195], v[194:195], 0, s[14:15]
	s_mov_b32 m0, s36
	ds_read_b128 v[186:189], v159 offset:49152
	ds_read_b128 v[190:193], v159 offset:50176
	ds_read_b128 v[198:201], v159 offset:51200
	ds_read_b128 v[202:205], v159 offset:52224
	ds_read_b128 v[206:209], v159 offset:53248
	ds_read_b128 v[210:213], v159 offset:54272
	ds_read_b128 v[214:217], v159 offset:55296
	ds_read_b128 v[218:221], v159 offset:56320
	global_load_lds_dwordx4 v[194:195], off
	s_add_i32 m0, s36, 0x2000
	s_add_u32 s34, s34, 0x40080
	v_lshl_add_u64 v[194:195], v[222:223], 0, s[14:15]
	s_addc_u32 s35, s35, 0
	s_add_i32 s36, s55, s33
	global_load_lds_dwordx4 v[194:195], off
	v_lshl_add_u64 v[194:195], s[34:35], 0, v[130:131]
	s_mov_b32 m0, s36
	s_nop 0
	global_load_lds_dwordx4 v[194:195], off
	v_lshl_add_u64 v[194:195], s[34:35], 0, v[134:135]
	s_add_i32 m0, s36, 0x2000
	s_nop 0
	global_load_lds_dwordx4 v[194:195], off
	v_lshl_add_u64 v[194:195], v[224:225], 0, s[14:15]
	s_mov_b32 m0, s44
	s_nop 0
	global_load_lds_dwordx4 v[194:195], off
	v_lshl_add_u64 v[194:195], v[226:227], 0, s[14:15]
	s_mov_b32 m0, s45
	s_nop 0
	global_load_lds_dwordx4 v[194:195], off
	s_waitcnt vmcnt(8)
	s_waitcnt lgkmcnt(0)
	s_barrier
	s_setprio 1
	s_waitcnt lgkmcnt(0)
	v_mfma_f32_16x16x32_bf16 v[92:95], v[144:147], v[186:189], v[92:95]
	v_mfma_f32_16x16x32_bf16 v[88:91], v[162:165], v[186:189], v[88:91]
	v_mfma_f32_16x16x32_bf16 v[84:87], v[144:147], v[198:201], v[84:87]
	v_mfma_f32_16x16x32_bf16 v[80:83], v[162:165], v[198:201], v[80:83]
	v_mfma_f32_16x16x32_bf16 v[76:79], v[144:147], v[206:209], v[76:79]
	v_mfma_f32_16x16x32_bf16 v[72:75], v[162:165], v[206:209], v[72:75]
	v_mfma_f32_16x16x32_bf16 v[68:71], v[144:147], v[214:217], v[68:71]
	v_mfma_f32_16x16x32_bf16 v[60:63], v[162:165], v[214:217], v[60:63]
	v_mfma_f32_16x16x32_bf16 v[92:95], v[148:151], v[190:193], v[92:95]
	v_mfma_f32_16x16x32_bf16 v[88:91], v[166:169], v[190:193], v[88:91]
	v_mfma_f32_16x16x32_bf16 v[84:87], v[148:151], v[202:205], v[84:87]
	v_mfma_f32_16x16x32_bf16 v[80:83], v[166:169], v[202:205], v[80:83]
	v_mfma_f32_16x16x32_bf16 v[76:79], v[148:151], v[210:213], v[76:79]
	v_mfma_f32_16x16x32_bf16 v[72:75], v[166:169], v[210:213], v[72:75]
	v_mfma_f32_16x16x32_bf16 v[68:71], v[148:151], v[218:221], v[68:71]
	v_mfma_f32_16x16x32_bf16 v[60:63], v[166:169], v[218:221], v[60:63]
	s_setprio 0
	s_setprio 1
	v_mfma_f32_16x16x32_bf16 v[28:31], v[170:173], v[186:189], v[28:31]
	v_mfma_f32_16x16x32_bf16 v[24:27], v[178:181], v[186:189], v[24:27]
	v_mfma_f32_16x16x32_bf16 v[20:23], v[170:173], v[198:201], v[20:23]
	v_mfma_f32_16x16x32_bf16 v[16:19], v[178:181], v[198:201], v[16:19]
	v_mfma_f32_16x16x32_bf16 v[12:15], v[170:173], v[206:209], v[12:15]
	v_mfma_f32_16x16x32_bf16 v[8:11], v[178:181], v[206:209], v[8:11]
	v_mfma_f32_16x16x32_bf16 v[4:7], v[170:173], v[214:217], v[4:7]
	v_mfma_f32_16x16x32_bf16 v[0:3], v[178:181], v[214:217], v[0:3]
	v_mfma_f32_16x16x32_bf16 v[28:31], v[174:177], v[190:193], v[28:31]
	v_mfma_f32_16x16x32_bf16 v[24:27], v[182:185], v[190:193], v[24:27]
	v_mfma_f32_16x16x32_bf16 v[20:23], v[174:177], v[202:205], v[20:23]
	v_mfma_f32_16x16x32_bf16 v[16:19], v[182:185], v[202:205], v[16:19]
	v_mfma_f32_16x16x32_bf16 v[12:15], v[174:177], v[210:213], v[12:15]
	v_mfma_f32_16x16x32_bf16 v[8:11], v[182:185], v[210:213], v[8:11]
	v_mfma_f32_16x16x32_bf16 v[4:7], v[174:177], v[218:221], v[4:7]
	v_mfma_f32_16x16x32_bf16 v[0:3], v[182:185], v[218:221], v[0:3]
	s_setprio 0
	s_barrier
	s_add_i32 s53, s53, 2
	s_add_u32 s30, s30, 0x100
	s_addc_u32 s31, s31, 0
	s_add_u32 s51, s51, 0x100
	s_addc_u32 s52, s52, 0
	s_cmp_gt_u32 s53, 13
	s_cbranch_scc0 .LBB0_525
	s_branch .Lrw1_x
.Lrw1_r0:
	s_waitcnt vmcnt(32)
	s_branch .Lrw1_b0

; #define PG8_BAR __builtin_amdgcn_s_barrier()
; template <class Epi, class Sched, bool ALIGN_EPI = false, bool SP2 = false>
; __device__ __forceinline__ void gemm_phase(PG8_LAS unsigned char* lds, const Gemm g, const Sched& S, const Epi& E) {
;     ...
;         if constexpr (ALIGN_EPI) { if (wr == 0) PG8_BAR; }
;         if constexpr (!Epi::AFTER_DRAIN) { E(acc, cur, wr, wc, fr, fq); S.done(cur); }
.Lrw1_x:
	s_and_b64 vcc, exec, s[16:17]
	s_cbranch_vccz .LBB0_528
	s_barrier

; #define PG8_STAGE(bufoff, gbase, voff) do { _Pragma("unroll") for (int _i = 0; _i < 2; ++_i) \
;         __builtin_amdgcn_global_load_lds((const unsigned*)((const char*)(gbase) + (voff)[_i]), (PG8_LAS unsigned*)(lds + (bufoff) + ldsw + _i * 8192), 16, 0, 0); } while (0)
; #define PG8_LDA(dst, b, h) do { _Pragma("unroll") for (int m = 0; m < 4; ++m) _Pragma("unroll") for (int k = 0; k < 2; ++k) dst[m][k] = *(const PG8_LAS bf16x8*)(lds + PG8_SA(b, h) + aoff + m * 2048 + k * 1024); } while (0)
; #define PG8_LDB(dst, b, h) do { _Pragma("unroll") for (int n = 0; n < 2; ++n) _Pragma("unroll") for (int k = 0; k < 2; ++k) dst[n][k] = *(const PG8_LAS bf16x8*)(lds + PG8_SB(b, h) + boff + n * 2048 + k * 1024); } while (0)
; #define PG8_SCHED __builtin_amdgcn_sched_barrier(0)
;     __device__ __forceinline__ void operator()(const f32x4 (&acc)[2][2][4][2], const Unit& u, int wr, int wc, int fr, int fq) const {
;     ...
;                 float h[8]; const float rsc = rs ? rs[row0 + ai * HALF + m * 16] : 1.0f;
; template <class Epi, class Sched, bool ALIGN_EPI = false, bool SP2 = false>
; __device__ __forceinline__ void gemm_phase(PG8_LAS unsigned char* lds, const Gemm g, const Sched& S, const Epi& E) {
;     ...
;         const bool has_next = S.next(ui + 1, nxt);
;         const char* nA = has_next ? (const char*)g.A + (size_t)nxt.pm * tstep : cA; const char* nB = has_next ? (const char*)g.Bt + (size_t)nxt.pn * tstep : cB;
;         for (int t = 0; t < nt; t += 2) {
;             const bool last = (t == nt - 2);
;             const char* a1 = cA + (size_t)(t + 1) * kstep;
;             const char* a2 = last ? nA : cA + (size_t)(t + 2) * kstep; const char* b2 = last ? nB : cB + (size_t)(t + 2) * kstep;
;             const char* a3 = a2 + kstep; const char* b3 = b2 + kstep;
;             if (last && has_next) S.a_ready(nxt);
;             if constexpr (SP2) {
;             PG8_LDB(B0, 0, 0); PG8_LDB(B1, 0, 1); PG8_SCHED; PG8_LDA(At, 0, 0); PG8_STAGE(PG8_SA(1, 1), a1 + hstep, voffA);
.LBB0_1145:
	s_ashr_i32 s19, s18, 31
	s_lshl_b64 s[20:21], s[18:19], 19
	s_add_u32 s20, s80, s20
	s_addc_u32 s21, s81, s21
	s_and_b64 s[22:23], s[0:1], exec
	s_cselect_b32 s3, s21, s27
	s_cselect_b32 s19, s20, s26
	s_ashr_i32 s17, s16, 31
	s_lshl_b64 s[22:23], s[16:17], 19
	s_add_u32 s22, s56, s22
	s_addc_u32 s23, s57, s23
	s_and_b64 s[30:31], s[0:1], exec
	s_cselect_b32 s17, s23, s29
	s_cselect_b32 s47, s22, s28
	s_add_u32 s26, s26, 0x40080
	s_addc_u32 s27, s27, 0
	s_add_u32 s48, s28, 0x100
	v_mov_b32_e32 v0, 0
	s_addc_u32 s49, s29, 0
	s_mov_b32 s50, -2
	v_mov_b32_e32 v1, v0
	v_mov_b32_e32 v2, v0
	v_mov_b32_e32 v3, v0
	v_mov_b32_e32 v8, v0
	v_mov_b32_e32 v9, v0
	v_mov_b32_e32 v10, v0
	v_mov_b32_e32 v11, v0
	v_mov_b32_e32 v16, v0
	v_mov_b32_e32 v17, v0
	v_mov_b32_e32 v18, v0
	v_mov_b32_e32 v19, v0
	v_mov_b32_e32 v24, v0
	v_mov_b32_e32 v25, v0
	v_mov_b32_e32 v26, v0
	v_mov_b32_e32 v27, v0
	v_mov_b32_e32 v32, v0
	v_mov_b32_e32 v33, v0
	v_mov_b32_e32 v34, v0
	v_mov_b32_e32 v35, v0
	v_mov_b32_e32 v40, v0
	v_mov_b32_e32 v41, v0
	v_mov_b32_e32 v42, v0
	v_mov_b32_e32 v43, v0
	v_mov_b32_e32 v48, v0
	v_mov_b32_e32 v49, v0
	v_mov_b32_e32 v50, v0
	v_mov_b32_e32 v51, v0
	v_mov_b32_e32 v56, v0
	v_mov_b32_e32 v57, v0
	v_mov_b32_e32 v58, v0
	v_mov_b32_e32 v59, v0
	v_mov_b32_e32 v4, v0
	v_mov_b32_e32 v5, v0
	v_mov_b32_e32 v6, v0
	v_mov_b32_e32 v7, v0
	v_mov_b32_e32 v12, v0
	v_mov_b32_e32 v13, v0
	v_mov_b32_e32 v14, v0
	v_mov_b32_e32 v15, v0
	v_mov_b32_e32 v20, v0
	v_mov_b32_e32 v21, v0
	v_mov_b32_e32 v22, v0
	v_mov_b32_e32 v23, v0
	v_mov_b32_e32 v28, v0
	v_mov_b32_e32 v29, v0
	v_mov_b32_e32 v30, v0
	v_mov_b32_e32 v31, v0
	v_mov_b32_e32 v36, v0
	v_mov_b32_e32 v37, v0
	v_mov_b32_e32 v38, v0
	v_mov_b32_e32 v39, v0
	v_mov_b32_e32 v44, v0
	v_mov_b32_e32 v45, v0
	v_mov_b32_e32 v46, v0
	v_mov_b32_e32 v47, v0
	v_mov_b32_e32 v52, v0
	v_mov_b32_e32 v53, v0
	v_mov_b32_e32 v54, v0
	v_mov_b32_e32 v55, v0
	v_mov_b32_e32 v60, v0
	v_mov_b32_e32 v61, v0
	v_mov_b32_e32 v62, v0
	v_mov_b32_e32 v63, v0
	v_mov_b32_e32 v64, v0
	v_mov_b32_e32 v65, v0
	v_mov_b32_e32 v66, v0
	v_mov_b32_e32 v67, v0
	v_mov_b32_e32 v72, v0
	v_mov_b32_e32 v73, v0
	v_mov_b32_e32 v74, v0
	v_mov_b32_e32 v75, v0
	v_mov_b32_e32 v80, v0
	v_mov_b32_e32 v81, v0
	v_mov_b32_e32 v82, v0
	v_mov_b32_e32 v83, v0
	v_mov_b32_e32 v88, v0
	v_mov_b32_e32 v89, v0
	v_mov_b32_e32 v90, v0
	v_mov_b32_e32 v91, v0
	v_mov_b32_e32 v96, v0
	v_mov_b32_e32 v97, v0
	v_mov_b32_e32 v98, v0
	v_mov_b32_e32 v99, v0
	v_mov_b32_e32 v104, v0
	v_mov_b32_e32 v105, v0
	v_mov_b32_e32 v106, v0
	v_mov_b32_e32 v107, v0
	v_mov_b32_e32 v112, v0
	v_mov_b32_e32 v113, v0
	v_mov_b32_e32 v114, v0
	v_mov_b32_e32 v115, v0
	v_mov_b32_e32 v120, v0
	v_mov_b32_e32 v121, v0
	v_mov_b32_e32 v122, v0
	v_mov_b32_e32 v123, v0
	v_mov_b32_e32 v68, v0
	v_mov_b32_e32 v69, v0
	v_mov_b32_e32 v70, v0
	v_mov_b32_e32 v71, v0
	v_mov_b32_e32 v76, v0
	v_mov_b32_e32 v77, v0
	v_mov_b32_e32 v78, v0
	v_mov_b32_e32 v79, v0
	v_mov_b32_e32 v84, v0
	v_mov_b32_e32 v85, v0
	v_mov_b32_e32 v86, v0
	v_mov_b32_e32 v87, v0
	v_mov_b32_e32 v92, v0
	v_mov_b32_e32 v93, v0
	v_mov_b32_e32 v94, v0
	v_mov_b32_e32 v95, v0
	v_mov_b32_e32 v100, v0
	v_mov_b32_e32 v101, v0
	v_mov_b32_e32 v102, v0
	v_mov_b32_e32 v103, v0
	v_mov_b32_e32 v108, v0
	v_mov_b32_e32 v109, v0
	v_mov_b32_e32 v110, v0
	v_mov_b32_e32 v111, v0
	v_mov_b32_e32 v116, v0
	v_mov_b32_e32 v117, v0
	v_mov_b32_e32 v118, v0
	v_mov_b32_e32 v119, v0
	v_mov_b32_e32 v124, v0
	v_mov_b32_e32 v125, v0
	v_mov_b32_e32 v126, v0
	v_mov_b32_e32 v127, v0
	v_lshl_add_u32 v146, s2, 8, v149
	v_ashrrev_i32_e32 v147, 31, v146
	v_lshl_add_u64 v[144:145], v[146:147], 2, s[4:5]
	global_load_dword v230, v[144:145], off
	global_load_dword v232, v[144:145], off offset:64
	global_load_dword v234, v[144:145], off offset:128
	global_load_dword v236, v[144:145], off offset:192
	global_load_dword v238, v[144:145], off offset:512
	global_load_dword v240, v[144:145], off offset:576
	global_load_dword v242, v[144:145], off offset:640
	global_load_dword v244, v[144:145], off offset:704
	s_cmp_eq_u32 s37, 1
	s_cselect_b32 s101, 0x7fffffff, -2
.LBB0_1146:
	ds_read_b128 v[144:147], v153
	ds_read_b128 v[156:159], v153 offset:1024
	ds_read_b128 v[160:163], v153 offset:2048
	ds_read_b128 v[164:167], v153 offset:3072
	ds_read_b128 v[168:171], v154
	ds_read_b128 v[172:175], v154 offset:1024
	ds_read_b128 v[176:179], v154 offset:2048
	ds_read_b128 v[180:183], v154 offset:3072
	s_add_u32 s28, s26, 0xfffc0080
	s_addc_u32 s29, s27, -1
	s_cmp_eq_u32 s50, 12
	s_cselect_b32 s31, s3, s29
	s_cselect_b32 s30, s19, s28
	s_cselect_b32 s29, s17, s49
	s_cselect_b32 s28, s47, s48
	v_lshl_add_u64 v[218:219], s[26:27], 0, v[136:137]
	s_add_i32 m0, s25, 0xc000
	ds_read_b128 v[184:187], v155
	ds_read_b128 v[188:191], v155 offset:1024
	ds_read_b128 v[192:195], v155 offset:2048
	ds_read_b128 v[198:201], v155 offset:3072
	ds_read_b128 v[202:205], v155 offset:4096
	ds_read_b128 v[206:209], v155 offset:5120
	ds_read_b128 v[210:213], v155 offset:6144
	ds_read_b128 v[214:217], v155 offset:7168
	global_load_lds_dwordx4 v[218:219], off
	v_lshl_add_u64 v[218:219], s[26:27], 0, v[138:139]
	s_add_i32 m0, s25, 0xe000
	s_nop 0
	global_load_lds_dwordx4 v[218:219], off
	s_cmp_eq_u32 s50, s101
	s_cbranch_scc1 .Lrw2_r0
	s_waitcnt vmcnt(8)
; #define PG8_STAGE(bufoff, gbase, voff) do { _Pragma("unroll") for (int _i = 0; _i < 2; ++_i) \
;         __builtin_amdgcn_global_load_lds((const unsigned*)((const char*)(gbase) + (voff)[_i]), (PG8_LAS unsigned*)(lds + (bufoff) + ldsw + _i * 8192), 16, 0, 0); } while (0)
; #define PG8_LDA(dst, b, h) do { _Pragma("unroll") for (int m = 0; m < 4; ++m) _Pragma("unroll") for (int k = 0; k < 2; ++k) dst[m][k] = *(const PG8_LAS bf16x8*)(lds + PG8_SA(b, h) + aoff + m * 2048 + k * 1024); } while (0)
; #define PG8_LDB(dst, b, h) do { _Pragma("unroll") for (int n = 0; n < 2; ++n) _Pragma("unroll") for (int k = 0; k < 2; ++k) dst[n][k] = *(const PG8_LAS bf16x8*)(lds + PG8_SB(b, h) + boff + n * 2048 + k * 1024); } while (0)
; #define PG8_MMA(ai, bj, At, Bt) do { __builtin_amdgcn_s_setprio(1); _Pragma("unroll") for (int m = 0; m < 4; ++m) _Pragma("unroll") for (int n = 0; n < 2; ++n) _Pragma("unroll") for (int k = 0; k < 2; ++k) \
;         acc[ai][bj][m][n] = __builtin_amdgcn_mfma_f32_16x16x32_bf16(Bt[n][k], At[m][k], acc[ai][bj][m][n], 0, 0, 0); __builtin_amdgcn_s_setprio(0); } while (0)
; #define PG8_WAIT_V(n) asm volatile("s_waitcnt vmcnt(" #n ")" ::: "memory")
; #define PG8_WAIT_L(n) asm volatile("s_waitcnt lgkmcnt(" #n ")" ::: "memory")
; #define PG8_BAR __builtin_amdgcn_s_barrier()
; #define PG8_SCHED __builtin_amdgcn_sched_barrier(0)
; template <class Epi, class Sched, bool ALIGN_EPI = false, bool SP2 = false>
; __device__ __forceinline__ void gemm_phase(PG8_LAS unsigned char* lds, const Gemm g, const Sched& S, const Epi& E) {
;     ...
;             PG8_LDB(B0, 0, 0); PG8_LDB(B1, 0, 1); PG8_SCHED; PG8_LDA(At, 0, 0); PG8_STAGE(PG8_SA(1, 1), a1 + hstep, voffA);
;             PG8_WAIT_V(8); PG8_WAIT_L(0); PG8_BAR; PG8_MMA(0, 0, At, B0); PG8_MMA(0, 1, At, B1); PG8_BAR; PG8_SCHED;
;             PG8_LDA(At, 0, 1); PG8_STAGE(PG8_SB(0, 0), b2, voffB); PG8_STAGE(PG8_SB(0, 1), b2 + hstep, voffB); PG8_STAGE(PG8_SA(0, 0), a2, voffA);
;             PG8_WAIT_V(8); PG8_WAIT_L(0); PG8_BAR; PG8_MMA(1, 0, At, B0); PG8_MMA(1, 1, At, B1); PG8_BAR; PG8_SCHED;
.Lrw2_b0:
	s_waitcnt lgkmcnt(0)
	s_barrier
	s_setprio 1
	s_waitcnt lgkmcnt(0)
	v_mfma_f32_16x16x32_bf16 v[124:127], v[144:147], v[184:187], v[124:127]
	v_mfma_f32_16x16x32_bf16 v[116:119], v[160:163], v[184:187], v[116:119]
	v_mfma_f32_16x16x32_bf16 v[108:111], v[144:147], v[192:195], v[108:111]
	v_mfma_f32_16x16x32_bf16 v[100:103], v[160:163], v[192:195], v[100:103]
	v_mfma_f32_16x16x32_bf16 v[92:95], v[144:147], v[202:205], v[92:95]
	v_mfma_f32_16x16x32_bf16 v[84:87], v[160:163], v[202:205], v[84:87]
	v_mfma_f32_16x16x32_bf16 v[76:79], v[144:147], v[210:213], v[76:79]
	v_mfma_f32_16x16x32_bf16 v[68:71], v[160:163], v[210:213], v[68:71]
	v_mfma_f32_16x16x32_bf16 v[124:127], v[156:159], v[188:191], v[124:127]
	v_mfma_f32_16x16x32_bf16 v[116:119], v[164:167], v[188:191], v[116:119]
	v_mfma_f32_16x16x32_bf16 v[108:111], v[156:159], v[198:201], v[108:111]
	v_mfma_f32_16x16x32_bf16 v[100:103], v[164:167], v[198:201], v[100:103]
	v_mfma_f32_16x16x32_bf16 v[92:95], v[156:159], v[206:209], v[92:95]
	v_mfma_f32_16x16x32_bf16 v[84:87], v[164:167], v[206:209], v[84:87]
	v_mfma_f32_16x16x32_bf16 v[76:79], v[156:159], v[214:217], v[76:79]
	v_mfma_f32_16x16x32_bf16 v[68:71], v[164:167], v[214:217], v[68:71]
	s_setprio 0
	s_setprio 1
	v_mfma_f32_16x16x32_bf16 v[120:123], v[168:171], v[184:187], v[120:123]
	v_mfma_f32_16x16x32_bf16 v[112:115], v[176:179], v[184:187], v[112:115]
	v_mfma_f32_16x16x32_bf16 v[104:107], v[168:171], v[192:195], v[104:107]
	v_mfma_f32_16x16x32_bf16 v[96:99], v[176:179], v[192:195], v[96:99]
	v_mfma_f32_16x16x32_bf16 v[88:91], v[168:171], v[202:205], v[88:91]
	v_mfma_f32_16x16x32_bf16 v[80:83], v[176:179], v[202:205], v[80:83]
	v_mfma_f32_16x16x32_bf16 v[72:75], v[168:171], v[210:213], v[72:75]
	v_mfma_f32_16x16x32_bf16 v[64:67], v[176:179], v[210:213], v[64:67]
	v_mfma_f32_16x16x32_bf16 v[120:123], v[172:175], v[188:191], v[120:123]
	v_mfma_f32_16x16x32_bf16 v[112:115], v[180:183], v[188:191], v[112:115]
	v_mfma_f32_16x16x32_bf16 v[104:107], v[172:175], v[198:201], v[104:107]
	v_mfma_f32_16x16x32_bf16 v[96:99], v[180:183], v[198:201], v[96:99]
	v_mfma_f32_16x16x32_bf16 v[88:91], v[172:175], v[206:209], v[88:91]
	v_mfma_f32_16x16x32_bf16 v[80:83], v[180:183], v[206:209], v[80:83]
	v_mfma_f32_16x16x32_bf16 v[72:75], v[172:175], v[214:217], v[72:75]
	v_mfma_f32_16x16x32_bf16 v[64:67], v[180:183], v[214:217], v[64:67]
	s_setprio 0
	s_barrier
	s_add_i32 s51, s44, s33
	v_lshl_add_u64 v[218:219], s[28:29], 0, v[130:131]
	s_mov_b32 m0, s51
	ds_read_b128 v[184:187], v155 offset:16384
	ds_read_b128 v[188:191], v155 offset:17408
	ds_read_b128 v[192:195], v155 offset:18432
	ds_read_b128 v[198:201], v155 offset:19456
	ds_read_b128 v[202:205], v155 offset:20480
	ds_read_b128 v[206:209], v155 offset:21504
	ds_read_b128 v[210:213], v155 offset:22528
	ds_read_b128 v[214:217], v155 offset:23552
	global_load_lds_dwordx4 v[218:219], off
	s_add_i32 m0, s51, 0x2000
	s_add_u32 s52, s28, 0x40000
	v_lshl_add_u64 v[220:221], s[28:29], 0, v[134:135]
	s_addc_u32 s53, s29, 0
	s_add_i32 s51, s45, s33
	global_load_lds_dwordx4 v[220:221], off
	v_lshl_add_u64 v[222:223], s[52:53], 0, v[130:131]
	s_mov_b32 m0, s51
	v_lshl_add_u64 v[224:225], s[30:31], 0, v[132:133]
	global_load_lds_dwordx4 v[222:223], off
	v_lshl_add_u64 v[222:223], s[52:53], 0, v[134:135]
	s_add_i32 m0, s51, 0x2000
	s_nop 0
	global_load_lds_dwordx4 v[222:223], off
	v_lshl_add_u64 v[222:223], s[30:31], 0, v[128:129]
	s_mov_b32 m0, s25
	s_nop 0
	global_load_lds_dwordx4 v[222:223], off
	s_mov_b32 m0, s34
	s_nop 0
	global_load_lds_dwordx4 v[224:225], off
	s_cmp_eq_u32 s50, s101
	s_cbranch_scc1 .Lrw2_r1
	s_waitcnt vmcnt(8)
.Lrw2_b1:
	s_waitcnt lgkmcnt(0)
	s_barrier
	s_setprio 1
	s_waitcnt lgkmcnt(0)
	v_mfma_f32_16x16x32_bf16 v[60:63], v[144:147], v[184:187], v[60:63]
	v_mfma_f32_16x16x32_bf16 v[52:55], v[160:163], v[184:187], v[52:55]
	v_mfma_f32_16x16x32_bf16 v[44:47], v[144:147], v[192:195], v[44:47]
	v_mfma_f32_16x16x32_bf16 v[36:39], v[160:163], v[192:195], v[36:39]
	v_mfma_f32_16x16x32_bf16 v[28:31], v[144:147], v[202:205], v[28:31]
	v_mfma_f32_16x16x32_bf16 v[20:23], v[160:163], v[202:205], v[20:23]
	v_mfma_f32_16x16x32_bf16 v[12:15], v[144:147], v[210:213], v[12:15]
	v_mfma_f32_16x16x32_bf16 v[4:7], v[160:163], v[210:213], v[4:7]
	v_mfma_f32_16x16x32_bf16 v[60:63], v[156:159], v[188:191], v[60:63]
	v_mfma_f32_16x16x32_bf16 v[52:55], v[164:167], v[188:191], v[52:55]
	v_mfma_f32_16x16x32_bf16 v[44:47], v[156:159], v[198:201], v[44:47]
	v_mfma_f32_16x16x32_bf16 v[36:39], v[164:167], v[198:201], v[36:39]
	v_mfma_f32_16x16x32_bf16 v[28:31], v[156:159], v[206:209], v[28:31]
	v_mfma_f32_16x16x32_bf16 v[20:23], v[164:167], v[206:209], v[20:23]
	v_mfma_f32_16x16x32_bf16 v[12:15], v[156:159], v[214:217], v[12:15]
	v_mfma_f32_16x16x32_bf16 v[4:7], v[164:167], v[214:217], v[4:7]
	s_setprio 0
	s_setprio 1
	v_mfma_f32_16x16x32_bf16 v[56:59], v[168:171], v[184:187], v[56:59]
	v_mfma_f32_16x16x32_bf16 v[48:51], v[176:179], v[184:187], v[48:51]
	v_mfma_f32_16x16x32_bf16 v[40:43], v[168:171], v[192:195], v[40:43]
	v_mfma_f32_16x16x32_bf16 v[32:35], v[176:179], v[192:195], v[32:35]
	v_mfma_f32_16x16x32_bf16 v[24:27], v[168:171], v[202:205], v[24:27]
	v_mfma_f32_16x16x32_bf16 v[16:19], v[176:179], v[202:205], v[16:19]
	v_mfma_f32_16x16x32_bf16 v[8:11], v[168:171], v[210:213], v[8:11]
	v_mfma_f32_16x16x32_bf16 v[0:3], v[176:179], v[210:213], v[0:3]
	v_mfma_f32_16x16x32_bf16 v[56:59], v[172:175], v[188:191], v[56:59]
	v_mfma_f32_16x16x32_bf16 v[48:51], v[180:183], v[188:191], v[48:51]
	v_mfma_f32_16x16x32_bf16 v[40:43], v[172:175], v[198:201], v[40:43]
	v_mfma_f32_16x16x32_bf16 v[32:35], v[180:183], v[198:201], v[32:35]
	v_mfma_f32_16x16x32_bf16 v[24:27], v[172:175], v[206:209], v[24:27]
	v_mfma_f32_16x16x32_bf16 v[16:19], v[180:183], v[206:209], v[16:19]
	v_mfma_f32_16x16x32_bf16 v[8:11], v[172:175], v[214:217], v[8:11]
	v_mfma_f32_16x16x32_bf16 v[0:3], v[180:183], v[214:217], v[0:3]
	s_setprio 0
	s_barrier
; #define PG8_STAGE(bufoff, gbase, voff) do { _Pragma("unroll") for (int _i = 0; _i < 2; ++_i) \
;         __builtin_amdgcn_global_load_lds((const unsigned*)((const char*)(gbase) + (voff)[_i]), (PG8_LAS unsigned*)(lds + (bufoff) + ldsw + _i * 8192), 16, 0, 0); } while (0)
; #define PG8_LDA(dst, b, h) do { _Pragma("unroll") for (int m = 0; m < 4; ++m) _Pragma("unroll") for (int k = 0; k < 2; ++k) dst[m][k] = *(const PG8_LAS bf16x8*)(lds + PG8_SA(b, h) + aoff + m * 2048 + k * 1024); } while (0)
; #define PG8_LDB(dst, b, h) do { _Pragma("unroll") for (int n = 0; n < 2; ++n) _Pragma("unroll") for (int k = 0; k < 2; ++k) dst[n][k] = *(const PG8_LAS bf16x8*)(lds + PG8_SB(b, h) + boff + n * 2048 + k * 1024); } while (0)
; #define PG8_MMA(ai, bj, At, Bt) do { __builtin_amdgcn_s_setprio(1); _Pragma("unroll") for (int m = 0; m < 4; ++m) _Pragma("unroll") for (int n = 0; n < 2; ++n) _Pragma("unroll") for (int k = 0; k < 2; ++k) \
;         acc[ai][bj][m][n] = __builtin_amdgcn_mfma_f32_16x16x32_bf16(Bt[n][k], At[m][k], acc[ai][bj][m][n], 0, 0, 0); __builtin_amdgcn_s_setprio(0); } while (0)
; #define PG8_WAIT_V(n) asm volatile("s_waitcnt vmcnt(" #n ")" ::: "memory")
; #define PG8_WAIT_L(n) asm volatile("s_waitcnt lgkmcnt(" #n ")" ::: "memory")
; #define PG8_BAR __builtin_amdgcn_s_barrier()
; #define PG8_SCHED __builtin_amdgcn_sched_barrier(0)
; template <class Epi, class Sched, bool ALIGN_EPI = false, bool SP2 = false>
; __device__ __forceinline__ void gemm_phase(PG8_LAS unsigned char* lds, const Gemm g, const Sched& S, const Epi& E) {
;     ...
;             PG8_LDB(B0, 1, 0); PG8_LDB(B1, 1, 1); PG8_SCHED; PG8_LDA(At, 1, 0); PG8_STAGE(PG8_SA(0, 1), a2 + hstep, voffA);
;             PG8_WAIT_V(8); PG8_WAIT_L(0); PG8_BAR; PG8_MMA(0, 0, At, B0); PG8_MMA(0, 1, At, B1); PG8_BAR; PG8_SCHED;
	s_add_i32 s51, 0, 0x18000
	v_add_u32_e32 v148, s51, v151
	s_add_i32 s52, 0, 0x1c000
	ds_read_b128 v[144:147], v148
	ds_read_b128 v[156:159], v148 offset:1024
	ds_read_b128 v[160:163], v148 offset:2048
	ds_read_b128 v[164:167], v148 offset:3072
	v_add_u32_e32 v148, s52, v151
	ds_read_b128 v[168:171], v148
	ds_read_b128 v[172:175], v148 offset:1024
	ds_read_b128 v[176:179], v148 offset:2048
	ds_read_b128 v[180:183], v148 offset:3072
	s_add_u32 s30, s30, 0x40000
	s_addc_u32 s31, s31, 0
	s_mov_b32 m0, s35
	v_lshl_add_u64 v[226:227], s[30:31], 0, v[128:129]
	ds_read_b128 v[184:187], v155 offset:32768
	ds_read_b128 v[188:191], v155 offset:33792
	ds_read_b128 v[192:195], v155 offset:34816
	ds_read_b128 v[198:201], v155 offset:35840
	ds_read_b128 v[202:205], v155 offset:36864
	ds_read_b128 v[206:209], v155 offset:37888
	ds_read_b128 v[210:213], v155 offset:38912
	ds_read_b128 v[214:217], v155 offset:39936
	global_load_lds_dwordx4 v[226:227], off
	v_lshl_add_u64 v[226:227], s[30:31], 0, v[132:133]
	s_mov_b32 m0, s36
	s_nop 0
	global_load_lds_dwordx4 v[226:227], off
	s_waitcnt vmcnt(8)
	s_waitcnt lgkmcnt(0)
	s_barrier
	s_setprio 1
	s_waitcnt lgkmcnt(0)
	v_mfma_f32_16x16x32_bf16 v[124:127], v[144:147], v[184:187], v[124:127]
	v_mfma_f32_16x16x32_bf16 v[116:119], v[160:163], v[184:187], v[116:119]
	v_mfma_f32_16x16x32_bf16 v[108:111], v[144:147], v[192:195], v[108:111]
	v_mfma_f32_16x16x32_bf16 v[100:103], v[160:163], v[192:195], v[100:103]
	v_mfma_f32_16x16x32_bf16 v[92:95], v[144:147], v[202:205], v[92:95]
	v_mfma_f32_16x16x32_bf16 v[84:87], v[160:163], v[202:205], v[84:87]
	v_mfma_f32_16x16x32_bf16 v[76:79], v[144:147], v[210:213], v[76:79]
	v_mfma_f32_16x16x32_bf16 v[68:71], v[160:163], v[210:213], v[68:71]
	v_mfma_f32_16x16x32_bf16 v[124:127], v[156:159], v[188:191], v[124:127]
	v_mfma_f32_16x16x32_bf16 v[116:119], v[164:167], v[188:191], v[116:119]
	v_mfma_f32_16x16x32_bf16 v[108:111], v[156:159], v[198:201], v[108:111]
	v_mfma_f32_16x16x32_bf16 v[100:103], v[164:167], v[198:201], v[100:103]
	v_mfma_f32_16x16x32_bf16 v[92:95], v[156:159], v[206:209], v[92:95]
	v_mfma_f32_16x16x32_bf16 v[84:87], v[164:167], v[206:209], v[84:87]
	v_mfma_f32_16x16x32_bf16 v[76:79], v[156:159], v[214:217], v[76:79]
	v_mfma_f32_16x16x32_bf16 v[68:71], v[164:167], v[214:217], v[68:71]
	s_setprio 0
	s_setprio 1
	v_mfma_f32_16x16x32_bf16 v[120:123], v[168:171], v[184:187], v[120:123]
	v_mfma_f32_16x16x32_bf16 v[112:115], v[176:179], v[184:187], v[112:115]
	v_mfma_f32_16x16x32_bf16 v[104:107], v[168:171], v[192:195], v[104:107]
	v_mfma_f32_16x16x32_bf16 v[96:99], v[176:179], v[192:195], v[96:99]
	v_mfma_f32_16x16x32_bf16 v[88:91], v[168:171], v[202:205], v[88:91]
	v_mfma_f32_16x16x32_bf16 v[80:83], v[176:179], v[202:205], v[80:83]
	v_mfma_f32_16x16x32_bf16 v[72:75], v[168:171], v[210:213], v[72:75]
	v_mfma_f32_16x16x32_bf16 v[64:67], v[176:179], v[210:213], v[64:67]
	v_mfma_f32_16x16x32_bf16 v[120:123], v[172:175], v[188:191], v[120:123]
	v_mfma_f32_16x16x32_bf16 v[112:115], v[180:183], v[188:191], v[112:115]
	v_mfma_f32_16x16x32_bf16 v[104:107], v[172:175], v[198:201], v[104:107]
	v_mfma_f32_16x16x32_bf16 v[96:99], v[180:183], v[198:201], v[96:99]
	v_mfma_f32_16x16x32_bf16 v[88:91], v[172:175], v[206:209], v[88:91]
	v_mfma_f32_16x16x32_bf16 v[80:83], v[180:183], v[206:209], v[80:83]
	v_mfma_f32_16x16x32_bf16 v[72:75], v[172:175], v[214:217], v[72:75]
	v_mfma_f32_16x16x32_bf16 v[64:67], v[180:183], v[214:217], v[64:67]
	s_setprio 0
	s_barrier
; #define PG8_STAGE(bufoff, gbase, voff) do { _Pragma("unroll") for (int _i = 0; _i < 2; ++_i) \
;         __builtin_amdgcn_global_load_lds((const unsigned*)((const char*)(gbase) + (voff)[_i]), (PG8_LAS unsigned*)(lds + (bufoff) + ldsw + _i * 8192), 16, 0, 0); } while (0)
; #define PG8_LDA(dst, b, h) do { _Pragma("unroll") for (int m = 0; m < 4; ++m) _Pragma("unroll") for (int k = 0; k < 2; ++k) dst[m][k] = *(const PG8_LAS bf16x8*)(lds + PG8_SA(b, h) + aoff + m * 2048 + k * 1024); } while (0)
; #define PG8_MMA(ai, bj, At, Bt) do { __builtin_amdgcn_s_setprio(1); _Pragma("unroll") for (int m = 0; m < 4; ++m) _Pragma("unroll") for (int n = 0; n < 2; ++n) _Pragma("unroll") for (int k = 0; k < 2; ++k) \
;         acc[ai][bj][m][n] = __builtin_amdgcn_mfma_f32_16x16x32_bf16(Bt[n][k], At[m][k], acc[ai][bj][m][n], 0, 0, 0); __builtin_amdgcn_s_setprio(0); } while (0)
; #define PG8_WAIT_V(n) asm volatile("s_waitcnt vmcnt(" #n ")" ::: "memory")
; #define PG8_WAIT_L(n) asm volatile("s_waitcnt lgkmcnt(" #n ")" ::: "memory")
; #define PG8_BAR __builtin_amdgcn_s_barrier()
; #define PG8_SCHED __builtin_amdgcn_sched_barrier(0)
; template <class Epi, class Sched, bool ALIGN_EPI = false, bool SP2 = false>
; __device__ __forceinline__ void gemm_phase(PG8_LAS unsigned char* lds, const Gemm g, const Sched& S, const Epi& E) {
;     ...
;             PG8_LDA(At, 1, 1); PG8_STAGE(PG8_SB(1, 0), b3, voffB); PG8_STAGE(PG8_SB(1, 1), b3 + hstep, voffB); PG8_STAGE(PG8_SA(1, 0), a3, voffA);
;             PG8_WAIT_V(8); PG8_WAIT_L(0); PG8_BAR; PG8_MMA(1, 0, At, B0); PG8_MMA(1, 1, At, B1); PG8_BAR; PG8_SCHED;
	s_add_i32 s30, s51, s33
	v_lshl_add_u64 v[218:219], v[218:219], 0, s[12:13]
	s_mov_b32 m0, s30
	ds_read_b128 v[184:187], v155 offset:49152
	ds_read_b128 v[188:191], v155 offset:50176
	ds_read_b128 v[192:195], v155 offset:51200
	ds_read_b128 v[198:201], v155 offset:52224
	ds_read_b128 v[202:205], v155 offset:53248
	ds_read_b128 v[206:209], v155 offset:54272
	ds_read_b128 v[210:213], v155 offset:55296
	ds_read_b128 v[214:217], v155 offset:56320
	global_load_lds_dwordx4 v[218:219], off
	s_add_i32 m0, s30, 0x2000
	s_add_u32 s28, s28, 0x40080
	v_lshl_add_u64 v[218:219], v[220:221], 0, s[12:13]
	s_addc_u32 s29, s29, 0
	s_add_i32 s30, s52, s33
	global_load_lds_dwordx4 v[218:219], off
	v_lshl_add_u64 v[218:219], s[28:29], 0, v[130:131]
	s_mov_b32 m0, s30
	s_nop 0
	global_load_lds_dwordx4 v[218:219], off
	v_lshl_add_u64 v[218:219], s[28:29], 0, v[134:135]
	s_add_i32 m0, s30, 0x2000
	s_nop 0
	global_load_lds_dwordx4 v[218:219], off
	v_lshl_add_u64 v[218:219], v[222:223], 0, s[12:13]
	s_mov_b32 m0, s40
	s_nop 0
	global_load_lds_dwordx4 v[218:219], off
	v_lshl_add_u64 v[218:219], v[224:225], 0, s[12:13]
	s_mov_b32 m0, s41
	s_nop 0
	global_load_lds_dwordx4 v[218:219], off
	s_waitcnt vmcnt(8)
	s_waitcnt lgkmcnt(0)
	s_barrier
	s_setprio 1
	s_waitcnt lgkmcnt(0)
	v_mfma_f32_16x16x32_bf16 v[60:63], v[144:147], v[184:187], v[60:63]
	v_mfma_f32_16x16x32_bf16 v[52:55], v[160:163], v[184:187], v[52:55]
	v_mfma_f32_16x16x32_bf16 v[44:47], v[144:147], v[192:195], v[44:47]
	v_mfma_f32_16x16x32_bf16 v[36:39], v[160:163], v[192:195], v[36:39]
	v_mfma_f32_16x16x32_bf16 v[28:31], v[144:147], v[202:205], v[28:31]
	v_mfma_f32_16x16x32_bf16 v[20:23], v[160:163], v[202:205], v[20:23]
	v_mfma_f32_16x16x32_bf16 v[12:15], v[144:147], v[210:213], v[12:15]
	v_mfma_f32_16x16x32_bf16 v[4:7], v[160:163], v[210:213], v[4:7]
	v_mfma_f32_16x16x32_bf16 v[60:63], v[156:159], v[188:191], v[60:63]
	v_mfma_f32_16x16x32_bf16 v[52:55], v[164:167], v[188:191], v[52:55]
	v_mfma_f32_16x16x32_bf16 v[44:47], v[156:159], v[198:201], v[44:47]
	v_mfma_f32_16x16x32_bf16 v[36:39], v[164:167], v[198:201], v[36:39]
	v_mfma_f32_16x16x32_bf16 v[28:31], v[156:159], v[206:209], v[28:31]
	v_mfma_f32_16x16x32_bf16 v[20:23], v[164:167], v[206:209], v[20:23]
	v_mfma_f32_16x16x32_bf16 v[12:15], v[156:159], v[214:217], v[12:15]
	v_mfma_f32_16x16x32_bf16 v[4:7], v[164:167], v[214:217], v[4:7]
	s_setprio 0
	s_setprio 1
	v_mfma_f32_16x16x32_bf16 v[56:59], v[168:171], v[184:187], v[56:59]
	v_mfma_f32_16x16x32_bf16 v[48:51], v[176:179], v[184:187], v[48:51]
	v_mfma_f32_16x16x32_bf16 v[40:43], v[168:171], v[192:195], v[40:43]
	v_mfma_f32_16x16x32_bf16 v[32:35], v[176:179], v[192:195], v[32:35]
	v_mfma_f32_16x16x32_bf16 v[24:27], v[168:171], v[202:205], v[24:27]
	v_mfma_f32_16x16x32_bf16 v[16:19], v[176:179], v[202:205], v[16:19]
	v_mfma_f32_16x16x32_bf16 v[8:11], v[168:171], v[210:213], v[8:11]
	v_mfma_f32_16x16x32_bf16 v[0:3], v[176:179], v[210:213], v[0:3]
	v_mfma_f32_16x16x32_bf16 v[56:59], v[172:175], v[188:191], v[56:59]
	v_mfma_f32_16x16x32_bf16 v[48:51], v[180:183], v[188:191], v[48:51]
	v_mfma_f32_16x16x32_bf16 v[40:43], v[172:175], v[198:201], v[40:43]
	v_mfma_f32_16x16x32_bf16 v[32:35], v[180:183], v[198:201], v[32:35]
	v_mfma_f32_16x16x32_bf16 v[24:27], v[172:175], v[206:209], v[24:27]
	v_mfma_f32_16x16x32_bf16 v[16:19], v[180:183], v[206:209], v[16:19]
	v_mfma_f32_16x16x32_bf16 v[8:11], v[172:175], v[214:217], v[8:11]
	v_mfma_f32_16x16x32_bf16 v[0:3], v[180:183], v[214:217], v[0:3]
	s_setprio 0
	s_barrier
	s_add_i32 s50, s50, 2
	s_add_u32 s26, s26, 0x100
	s_addc_u32 s27, s27, 0
	s_add_u32 s48, s48, 0x100
	s_addc_u32 s49, s49, 0
	s_cmp_gt_u32 s50, 13
	s_cbranch_scc0 .LBB0_1146
	s_branch .Lrw2_x
.Lrw2_r0:
	s_waitcnt vmcnt(24)
	s_branch .Lrw2_b0

; #define PG8_BAR __builtin_amdgcn_s_barrier()
; template <class Epi, class Sched, bool ALIGN_EPI = false, bool SP2 = false>
; __device__ __forceinline__ void gemm_phase(PG8_LAS unsigned char* lds, const Gemm g, const Sched& S, const Epi& E) {
;     ...
;         if constexpr (ALIGN_EPI) { if (wr == 0) PG8_BAR; }
;         if constexpr (!Epi::AFTER_DRAIN) { E(acc, cur, wr, wc, fr, fq); S.done(cur); }
.Lrw2_x:
	s_and_b64 vcc, exec, s[14:15]
	s_cbranch_vccz .LBB0_1149
	s_barrier
